# attnA LDS-read pipelining + packed-f32 split, in-proj K-loop DMA interleaved with MFMAs, in-proj epilogue: bias loaded once per tile, per-j vmcnt(0) drains removed
# speedup vs baseline: 1.0312x; 1.0312x over previous
; template <int WM, class Epi>
; DI void gemm_mfma(const bf16_t* __restrict__ A, const bf16_t* __restrict__ Bt, int Arows, int Brows, int MT, int NT, unsigned char* smem, int bid, int nb, int wave, Epi epi) {
;     ...
;     auto issue = [&](int kt, int buf) {
; #pragma unroll
;       for (int i = 0; i < NAW; ++i)
;         __builtin_amdgcn_global_load_lds((const unsigned*)(abase + kt * astep + i * 1024 + voff),
;                                          (__attribute__((address_space(3))) unsigned*)(smem + buf * STAGE + (wvu * NAW + i) * 1024), 16, 0, 0);
; #pragma unroll
;       for (int i = 0; i < 2; ++i)
;         __builtin_amdgcn_global_load_lds((const unsigned*)(bbase + kt * bstep + i * 1024 + voff),
;                                          (__attribute__((address_space(3))) unsigned*)(smem + buf * STAGE + A_BYTES + (wvu * 2 + i) * 1024), 16, 0, 0);
;     };
;     RAW_BARRIER();
;     constexpr int NST = (WM == 2) ? 4 : 3;
;     constexpr int NKT = K / 32;
; #pragma unroll
;     for (int s = 0; s < NST - 1; ++s) issue(s, s);
;     bf16x8 fa0[WM], fb0[2], fa1[WM], fb1[2];
; #pragma unroll
;     for (int mi = 0; mi < WM; ++mi) { fa0[mi] = bf16x8{0, 0, 0, 0, 0, 0, 0, 0}; fa1[mi] = fa0[mi]; }
;     fb0[0] = bf16x8{0, 0, 0, 0, 0, 0, 0, 0}; fb0[1] = fb0[0]; fb1[0] = fb0[0]; fb1[1] = fb0[0];
;     ...
; #pragma unroll 1
;     for (int kt = 0; kt < NKT; ++kt) {
;       const int ahead = (NKT - 1 - kt < NST - 2) ? (NKT - 1 - kt) : (NST - 2);
;       if (NI == 4) { if (ahead == 2) asm volatile("s_waitcnt vmcnt(8)" ::: "memory"); else if (ahead == 1) asm volatile("s_waitcnt vmcnt(4)" ::: "memory"); else asm volatile("s_waitcnt vmcnt(0)" ::: "memory"); }
;       else { if (ahead == 1) asm volatile("s_waitcnt vmcnt(6)" ::: "memory"); else asm volatile("s_waitcnt vmcnt(0)" ::: "memory"); }
;       RAW_BARRIER();
;       if (kt + NST - 1 < NKT) issue(kt + NST - 1, (kt + NST - 1) % NST);
;       const unsigned sb = lds0 + (unsigned)((kt % NST) * STAGE);
;       const unsigned a0 = sb + offA0, a1 = sb + offA1, b0 = sb + offB0, b1 = sb + offB1;
;       if constexpr (WM == 4) GEMM_READ4(a0, b0, fa0, fb0); else GEMM_READ2(a0, b0, fa0, fb0);
;       GEMM_MMA(fa1, fb1);
;       if constexpr (WM == 4) { GEMM_WAIT4(fa0, fb0); GEMM_READ4(a1, b1, fa1, fb1); } else { GEMM_WAIT2(fa0, fb0); GEMM_READ2(a1, b1, fa1, fb1); }
;       GEMM_MMA(fa0, fb0);
;     }
.LBB0_169:
	s_waitcnt lgkmcnt(0)
	s_add_i32 s6, s21, -2
	s_cmp_gt_u32 s6, 29
	s_barrier
	s_cbranch_scc1 .LBB0_164
	s_mul_i32 s7, s21, 0xab
	s_bfe_u32 s7, s7, 0x70009
	s_mul_i32 s7, s7, 3
	s_sub_i32 s7, s21, s7
	s_and_b32 s7, s7, 0xff
	s_mulk_i32 s7, 0x6000
	s_add_i32 s25, s7, s9
	s_add_i32 s7, s7, s20
	s_mul_i32 s26, s6, 0xab
	s_bfe_u32 s26, s26, 0x70009
	s_mul_i32 s26, s26, 3
	s_sub_i32 s6, s6, s26
	s_and_b32 s6, s6, 0xff
	s_mulk_i32 s6, 0x6000
	v_add_u32_e32 v160, s6, v159
	v_add_u32_e32 v170, s6, v165
	ds_read_b128 v[196:199], v160
	ds_read_b128 v[200:203], v160 offset:2048
	ds_read_b128 v[204:207], v160 offset:4096
	ds_read_b128 v[208:211], v160 offset:6144
	ds_read_b128 v[212:215], v170
	ds_read_b128 v[216:219], v170 offset:2048
	v_lshl_add_u64 v[224:225], s[0:1], 0, v[154:155]
	v_lshl_add_u64 v[220:221], s[4:5], 0, v[154:155]
	s_mov_b64 s[26:27], 0x8c000
	v_lshl_add_u64 v[222:223], v[224:225], 0, s[26:27]
	s_add_i32 m0, s7, 0x4000
	s_setprio 1
	v_mfma_f32_32x32x16_bf16 v[112:127], v[148:151], v[144:147], v[112:127]
	global_load_lds_dwordx4 v[222:223], off
	v_add_u32_e32 v160, s6, v164
	v_add_u32_e32 v170, s6, v166
	s_mov_b64 s[26:27], 0x8c400
	v_lshl_add_u64 v[222:223], v[224:225], 0, s[26:27]
	s_add_i32 m0, s7, 0x4400
	v_mfma_f32_32x32x16_bf16 v[96:111], v[148:151], v[136:139], v[96:111]
	v_mfma_f32_32x32x16_bf16 v[80:95], v[140:143], v[144:147], v[80:95]
	global_load_lds_dwordx4 v[222:223], off
	v_lshl_add_u64 v[222:223], v[220:221], 0, s[40:41]
	s_mov_b32 m0, s25
	v_mfma_f32_32x32x16_bf16 v[64:79], v[140:143], v[136:139], v[64:79]
	v_mfma_f32_32x32x16_bf16 v[48:63], v[132:135], v[144:147], v[48:63]
	global_load_lds_dwordx4 v[222:223], off
	s_mov_b64 s[26:27], 0x2006400
	v_lshl_add_u64 v[222:223], v[220:221], 0, s[26:27]
	s_add_i32 m0, s25, 0x400
	v_mfma_f32_32x32x16_bf16 v[32:47], v[132:135], v[136:139], v[32:47]
	v_mfma_f32_32x32x16_bf16 v[16:31], v[128:131], v[144:147], v[16:31]
	global_load_lds_dwordx4 v[222:223], off
	s_mov_b64 s[26:27], 0x2006800
	v_lshl_add_u64 v[222:223], v[220:221], 0, s[26:27]
	s_add_i32 m0, s25, 0x800
	v_mfma_f32_32x32x16_bf16 v[0:15], v[128:131], v[136:139], v[0:15]
	s_setprio 0
	s_waitcnt lgkmcnt(0)
	ds_read_b128 v[148:151], v160
	ds_read_b128 v[140:143], v160 offset:2048
	ds_read_b128 v[132:135], v160 offset:4096
	ds_read_b128 v[128:131], v160 offset:6144
	ds_read_b128 v[144:147], v170
	ds_read_b128 v[136:139], v170 offset:2048
	s_setprio 1
	v_mfma_f32_32x32x16_bf16 v[112:127], v[196:199], v[212:215], v[112:127]
	global_load_lds_dwordx4 v[222:223], off
	s_mov_b64 s[26:27], 0x2006c00
	v_lshl_add_u64 v[222:223], v[220:221], 0, s[26:27]
	s_add_i32 m0, s25, 0xc00
	v_mfma_f32_32x32x16_bf16 v[96:111], v[196:199], v[216:219], v[96:111]
	v_mfma_f32_32x32x16_bf16 v[80:95], v[200:203], v[212:215], v[80:95]
	global_load_lds_dwordx4 v[222:223], off
	v_mfma_f32_32x32x16_bf16 v[64:79], v[200:203], v[216:219], v[64:79]
	v_mfma_f32_32x32x16_bf16 v[48:63], v[204:207], v[212:215], v[48:63]
	v_mfma_f32_32x32x16_bf16 v[32:47], v[204:207], v[216:219], v[32:47]
	v_mfma_f32_32x32x16_bf16 v[16:31], v[208:211], v[212:215], v[16:31]
	v_mfma_f32_32x32x16_bf16 v[0:15], v[208:211], v[216:219], v[0:15]
	s_setprio 0
	s_add_u32 s0, s0, 0x46000
	s_addc_u32 s1, s1, 0
	s_add_u32 s4, s4, 0x120000
	s_addc_u32 s5, s5, 0
	s_add_i32 s21, s21, 1
	s_branch .LBB0_165
; #define RAW_BARRIER() do { asm volatile("s_waitcnt lgkmcnt(0)" ::: "memory"); __builtin_amdgcn_s_barrier(); } while (0)
; #define GEMM_WAIT4(FA, FB) asm volatile("s_waitcnt lgkmcnt(0)" : "+v"(FA[0]), "+v"(FA[1]), "+v"(FA[2]), "+v"(FA[3]), "+v"(FB[0]), "+v"(FB[1]) :: "memory")
; #define GEMM_WAIT2(FA, FB) asm volatile("s_waitcnt lgkmcnt(0)" : "+v"(FA[0]), "+v"(FA[1]), "+v"(FB[0]), "+v"(FB[1]) :: "memory")
; template <int WM, class Epi>
; DI void gemm_mfma(const bf16_t* __restrict__ A, const bf16_t* __restrict__ Bt, int Arows, int Brows, int MT, int NT, unsigned char* smem, int bid, int nb, int wave, Epi epi) {
;     ...
;     if constexpr (WM == 4) GEMM_WAIT4(fa1, fb1); else GEMM_WAIT2(fa1, fb1);
;     GEMM_MMA(fa1, fb1);
;     int r2 = r, h2 = h;
;     asm volatile("" : "+v"(r2), "+v"(h2));
;     epi(mt, nt, wm, wn, r2, h2, acc);
;   }
; }
;   DI void operator()(int mt, int nt, int wm, int wn, int r, int h, f32x16 (&acc)[WM][2]) const {
;     constexpr int LD = 132;
;     float* T = (float*)smem;
;     const int tid = wm * 128 + wn * 64 + h * 32 + r;
; #pragma unroll
;     for (int ps = 0; ps < WM / 2; ++ps) {
;       RAW_BARRIER();
; #pragma unroll
;       for (int mh = 0; mh < 2; ++mh)
; #pragma unroll
;         for (int ni = 0; ni < 2; ++ni)
; #pragma unroll
;           for (int i = 0; i < 16; ++i)
;             T[(wm * 64 + mh * 32 + (i & 3) + 8 * (i >> 2) + 4 * h) * LD + wn * 64 + ni * 32 + r] = acc[ps * 2 + mh][ni][i];
;       RAW_BARRIER();
;       const int ropemode0 = (nt < 4) ? 1 : ((nt >= 14 && nt <= 16) ? 2 : 0);
; #pragma unroll
;       for (int j = 0; j < 8; ++j) {
;         const int id = tid + 256 * j;
;         const int lr = id >> 4, cc = id & 15;
;         const int row = mt * (WM * 64) + (lr >> 6) * (WM * 32) + ps * 64 + (lr & 63);
;         const int col0 = nt * 128 + cc * 8;
;         if (col0 < PW) {
;           const int t = row % NTOK;
;           const int ropemode = (t >= NCTX) ? ropemode0 : 0;
;           const float4 a0 = *(const float4*)(T + lr * LD + cc * 8), a1 = *(const float4*)(T + lr * LD + cc * 8 + 4);
;           const float4 b0 = *(const float4*)(bias + col0), b1 = *(const float4*)(bias + col0 + 4);
;           float v[8] = {a0.x + b0.x, a0.y + b0.y, a0.z + b0.z, a0.w + b0.w, a1.x + b1.x, a1.y + b1.y, a1.z + b1.z, a1.w + b1.w};
.LBB0_171:
	s_waitcnt lgkmcnt(0)
	s_setprio 1
	v_mfma_f32_32x32x16_bf16 v[112:127], v[148:151], v[144:147], v[112:127]
	v_mfma_f32_32x32x16_bf16 v[96:111], v[148:151], v[136:139], v[96:111]
	v_mfma_f32_32x32x16_bf16 v[80:95], v[140:143], v[144:147], v[80:95]
	v_mfma_f32_32x32x16_bf16 v[48:63], v[132:135], v[144:147], v[48:63]
	v_mfma_f32_32x32x16_bf16 v[32:47], v[132:135], v[136:139], v[32:47]
	v_mfma_f32_32x32x16_bf16 v[16:31], v[128:131], v[144:147], v[16:31]
	v_mfma_f32_32x32x16_bf16 v[0:15], v[128:131], v[136:139], v[0:15]
	v_mfma_f32_32x32x16_bf16 v[64:79], v[140:143], v[136:139], v[64:79]
	s_setprio 0
	s_sext_i32_i16 s4, s29
	s_cmp_lt_i32 s4, 4
	s_cselect_b64 s[44:45], -1, 0
	s_sub_i32 s0, s8, 17
	s_cmp_lt_u32 s0, -3
	s_cselect_b64 s[0:1], -1, 0
	s_cmp_gt_i32 s4, 3
	s_cselect_b64 s[4:5], -1, 0
	s_and_b64 s[8:9], s[4:5], exec
	v_mov_b32_e32 v133, v157
	v_mov_b32_e32 v128, v158
	s_cselect_b32 s8, 2, 1
	v_cndmask_b32_e64 v137, 0, 1, s[4:5]
	v_bitop3_b32 v131, v133, s8, 15 bitop3:0x6c
	v_lshlrev_b32_e32 v132, 3, v131
	v_lshrrev_b32_e32 v131, v137, v133
	v_lshlrev_b32_e32 v129, 5, v128
	v_and_b32_e32 v131, 2, v131
	v_add3_u32 v204, v168, v133, v129
	v_lshl_add_u32 v134, v128, 2, v169
	v_add_u32_e32 v135, v133, v167
	v_and_b32_e32 v136, 15, v133
	s_and_b64 s[46:47], s[4:5], s[0:1]
	v_cmp_eq_u32_e64 s[4:5], 0, v131
	v_lshlrev_b32_e32 v131, 3, v133
	v_bfe_u32 v133, v133, v137, 1
	v_cmp_eq_u32_e64 s[0:1], 0, v133
	v_mul_lo_u32 v133, v134, s66
	v_lshl_add_u32 v133, v135, 2, v133
	s_waitcnt lgkmcnt(0)
	s_barrier
	s_waitcnt vmcnt(0)
	ds_write2_b32 v133, v112, v96 offset1:32
	ds_write2_b32 v133, v113, v97 offset0:132 offset1:164
	v_add_u32_e32 v112, 0x400, v133
	ds_write2_b32 v112, v114, v98 offset0:8 offset1:40
	ds_write2_b32 v112, v115, v99 offset0:140 offset1:172
	v_add_u32_e32 v113, 0x1000, v133
	v_add_u32_e32 v114, 0x1400, v133
	v_add_u32_e32 v115, 0x2000, v133
	ds_write2_b32 v113, v116, v100 offset0:32 offset1:64
	ds_write2_b32 v113, v117, v101 offset0:164 offset1:196
	ds_write2_b32 v114, v118, v102 offset0:40 offset1:72
	ds_write2_b32 v114, v119, v103 offset0:172 offset1:204
	ds_write2_b32 v115, v120, v104 offset0:64 offset1:96
	ds_write2_b32 v115, v121, v105 offset0:196 offset1:228
	v_add_u32_e32 v116, 0x2400, v133
	v_add_u32_e32 v117, 0x3000, v133
	v_add_u32_e32 v119, 0x3400, v133
	v_add_u32_e32 v120, 0x3600, v133
	v_lshlrev_b32_e32 v130, 3, v136
	v_cmp_gt_u32_e32 vcc, 2, v136
	ds_write2_b32 v116, v122, v106 offset0:72 offset1:104
	ds_write2_b32 v116, v123, v107 offset0:204 offset1:236
	ds_write2_b32 v117, v124, v108 offset0:96 offset1:128
	v_add_u32_e32 v118, 0x3200, v133
	ds_write2_b32 v119, v126, v110 offset0:104 offset1:136
	ds_write2_b32 v120, v127, v111 offset0:108 offset1:140
	v_add_u32_e32 v121, 0x4000, v133
	v_add_u32_e32 v122, 0x4400, v133
	v_add_u32_e32 v124, 0x4800, v133
	v_add_u32_e32 v126, 0x5000, v133
	v_add_u32_e32 v127, 0x5400, v133
	v_add_u32_e32 v134, 0x5800, v133
	v_add_u32_e32 v135, 0x6000, v133
	v_add_u32_e32 v136, 0x6400, v133
	v_add_u32_e32 v137, 0x6800, v133
	v_add_u32_e32 v139, 0x7200, v133
	v_add_u32_e32 v141, 0x7400, v133
	v_add_u32_e32 v142, 0x7600, v133
	v_add_u32_e32 v143, 0x7800, v133
	s_ashr_i32 s25, s24, 31
	s_and_b32 s43, 0xffff, s29
	ds_write2_b32 v118, v125, v109 offset0:100 offset1:132
	ds_write2_b32 v121, v80, v64 offset0:128 offset1:160
	ds_write2_b32 v122, v81, v65 offset0:4 offset1:36
	ds_write2_b32 v122, v82, v66 offset0:136 offset1:168
	ds_write2_b32 v124, v83, v67 offset0:12 offset1:44
	ds_write2_b32 v126, v84, v68 offset0:160 offset1:192
	ds_write2_b32 v127, v85, v69 offset0:36 offset1:68
	ds_write2_b32 v127, v86, v70 offset0:168 offset1:200
	ds_write2_b32 v134, v87, v71 offset0:44 offset1:76
	ds_write2_b32 v135, v88, v72 offset0:192 offset1:224
	ds_write2_b32 v136, v89, v73 offset0:68 offset1:100
	ds_write2_b32 v136, v90, v74 offset0:200 offset1:232
	ds_write2_b32 v137, v91, v75 offset0:76 offset1:108
	ds_write2_b32 v139, v92, v76 offset0:96 offset1:128
	ds_write2_b32 v141, v93, v77 offset0:100 offset1:132
	ds_write2_b32 v142, v94, v78 offset0:104 offset1:136
	ds_write2_b32 v143, v95, v79 offset0:108 offset1:140
	v_or_b32_e32 v128, s24, v130
	s_cmp_eq_u32 s43, 24
	s_waitcnt lgkmcnt(0)
	v_ashrrev_i32_e32 v94, 4, v204
	v_ashrrev_i32_e32 v64, 3, v204
	v_ashrrev_i32_e32 v129, 31, v128
	s_cselect_b64 s[8:9], -1, 0
	v_and_b32_e32 v144, 0xffffff80, v64
	v_mul_lo_u32 v102, v94, s66
	v_cmp_gt_i32_e64 s[6:7], s63, v128
	v_and_b32_e32 v131, 8, v131
	s_and_b64 s[40:41], s[8:9], vcc
	v_add_u32_e32 v205, s28, v144
	v_and_b32_e32 v110, 63, v94
	v_lshl_add_u32 v111, v130, 2, v102
	v_lshl_add_u64 v[88:89], v[128:129], 2, s[14:15]
	s_barrier
	s_and_saveexec_b64 s[8:9], s[6:7]
	s_cbranch_execz .LBB0_180
	global_load_dwordx4 v[220:223], v[88:89], off
	global_load_dwordx4 v[224:227], v[88:89], off offset:16
	v_or_b32_e32 v90, v205, v110
	v_mul_hi_i32 v80, v90, s55
	ds_read_b128 v[68:71], v111
	ds_read_b128 v[76:79], v111 offset:16
	v_lshrrev_b32_e32 v81, 31, v80
	v_ashrrev_i32_e32 v80, 9, v80
	v_add_u32_e32 v80, v80, v81
	v_mul_i32_i24_e32 v80, 0x900, v80
	v_sub_u32_e32 v91, v90, v80
	s_xor_b64 s[20:21], s[46:47], -1
	v_cmp_lt_i32_e32 vcc, s62, v91
	s_and_b64 s[26:27], vcc, s[20:21]
	s_waitcnt vmcnt(0) lgkmcnt(0)
	v_pk_add_f32 v[68:69], v[68:69], v[220:221]
	v_pk_add_f32 v[70:71], v[70:71], v[222:223]
	v_pk_add_f32 v[64:65], v[76:77], v[224:225]
	v_pk_add_f32 v[66:67], v[78:79], v[226:227]
	s_and_saveexec_b64 s[20:21], s[26:27]
	s_cbranch_execz .LBB0_178
	s_lshl_b64 s[26:27], s[24:25], 2
	s_add_u32 s26, s14, s26
	v_lshlrev_b32_e32 v76, 2, v132
	s_addc_u32 s27, s15, s27
	global_load_dwordx4 v[72:75], v76, s[26:27] offset:16
	global_load_dwordx4 v[80:83], v76, s[26:27]
	v_add_u32_e32 v76, v102, v76
	ds_read_b128 v[84:87], v76
	ds_read_b128 v[76:79], v76 offset:16
	v_add_u32_e32 v92, 0xffffff00, v91
	v_lshrrev_b32_e32 v92, 6, v92
	v_and_b32_e32 v91, 63, v91
	v_cndmask_b32_e64 v91, v91, v92, s[4:5]
	s_andn2_b64 vcc, exec, s[44:45]
	s_mov_b64 s[26:27], -1
	s_cbranch_vccnz .LBB0_175
	v_lshlrev_b32_e32 v160, 6, v91
	v_lshl_add_u64 v[92:93], s[18:19], 0, v[160:161]
	s_mov_b64 s[26:27], 0

;   DI void operator()(int mt, int nt, int wm, int wn, int r, int h, f32x16 (&acc)[WM][2]) const {
;     ...
;       for (int j = 0; j < 8; ++j) {
;         const int id = tid + 256 * j;
;         const int lr = id >> 4, cc = id & 15;
;         const int row = mt * (WM * 64) + (lr >> 6) * (WM * 32) + ps * 64 + (lr & 63);
;         const int col0 = nt * 128 + cc * 8;
;         if (col0 < PW) {
;           const int t = row % NTOK;
;           const int ropemode = (t >= NCTX) ? ropemode0 : 0;
;           const float4 a0 = *(const float4*)(T + lr * LD + cc * 8), a1 = *(const float4*)(T + lr * LD + cc * 8 + 4);
;           const float4 b0 = *(const float4*)(bias + col0), b1 = *(const float4*)(bias + col0 + 4);
;           float v[8] = {a0.x + b0.x, a0.y + b0.y, a0.z + b0.z, a0.w + b0.w, a1.x + b1.x, a1.y + b1.y, a1.z + b1.z, a1.w + b1.w};
.LBB0_180:
	s_or_b64 exec, exec, s[8:9]
	s_nop 0
	v_add_u32_e32 v64, 0x100, v204
	v_ashrrev_i32_e32 v95, 4, v64
	v_ashrrev_i32_e32 v64, 3, v64
	v_and_b32_e32 v147, 0xffffff80, v64
	v_mul_lo_u32 v103, v95, s66
	v_add_u32_e32 v206, s28, v147
	v_and_b32_e32 v123, 63, v95
	v_lshl_add_u32 v125, v130, 2, v103
	s_and_saveexec_b64 s[8:9], s[6:7]
	s_cbranch_execz .LBB0_189
	v_or_b32_e32 v90, v206, v123
	v_mul_hi_i32 v80, v90, s55
	ds_read_b128 v[68:71], v125
	ds_read_b128 v[76:79], v125 offset:16
	v_lshrrev_b32_e32 v81, 31, v80
	v_ashrrev_i32_e32 v80, 9, v80
	v_add_u32_e32 v80, v80, v81
	v_mul_i32_i24_e32 v80, 0x900, v80
	v_sub_u32_e32 v91, v90, v80
	s_xor_b64 s[20:21], s[46:47], -1
	v_cmp_lt_i32_e32 vcc, s62, v91
	s_and_b64 s[26:27], vcc, s[20:21]
	s_waitcnt lgkmcnt(0)
	v_pk_add_f32 v[68:69], v[68:69], v[220:221]
	v_pk_add_f32 v[70:71], v[70:71], v[222:223]
	v_pk_add_f32 v[64:65], v[76:77], v[224:225]
	v_pk_add_f32 v[66:67], v[78:79], v[226:227]
	s_and_saveexec_b64 s[20:21], s[26:27]
	s_cbranch_execz .LBB0_187
	s_lshl_b64 s[26:27], s[24:25], 2
	s_add_u32 s26, s14, s26
	v_lshlrev_b32_e32 v76, 2, v132
	s_addc_u32 s27, s15, s27
	global_load_dwordx4 v[72:75], v76, s[26:27] offset:16
	global_load_dwordx4 v[80:83], v76, s[26:27]
	v_add_u32_e32 v76, v103, v76
	ds_read_b128 v[84:87], v76
	ds_read_b128 v[76:79], v76 offset:16
	v_add_u32_e32 v92, 0xffffff00, v91
	v_lshrrev_b32_e32 v92, 6, v92
	v_and_b32_e32 v91, 63, v91
	v_cndmask_b32_e64 v91, v91, v92, s[4:5]
	s_andn2_b64 vcc, exec, s[44:45]
	s_mov_b64 s[26:27], -1
	s_cbranch_vccnz .LBB0_184
	v_lshlrev_b32_e32 v160, 6, v91
	v_lshl_add_u64 v[92:93], s[18:19], 0, v[160:161]
	s_mov_b64 s[26:27], 0

;   DI void operator()(int mt, int nt, int wm, int wn, int r, int h, f32x16 (&acc)[WM][2]) const {
;     ...
;       for (int j = 0; j < 8; ++j) {
;         const int id = tid + 256 * j;
;         const int lr = id >> 4, cc = id & 15;
;         const int row = mt * (WM * 64) + (lr >> 6) * (WM * 32) + ps * 64 + (lr & 63);
;         const int col0 = nt * 128 + cc * 8;
;         if (col0 < PW) {
;           const int t = row % NTOK;
;           const int ropemode = (t >= NCTX) ? ropemode0 : 0;
;           const float4 a0 = *(const float4*)(T + lr * LD + cc * 8), a1 = *(const float4*)(T + lr * LD + cc * 8 + 4);
;           const float4 b0 = *(const float4*)(bias + col0), b1 = *(const float4*)(bias + col0 + 4);
;           float v[8] = {a0.x + b0.x, a0.y + b0.y, a0.z + b0.z, a0.w + b0.w, a1.x + b1.x, a1.y + b1.y, a1.z + b1.z, a1.w + b1.w};
.LBB0_189:
	s_or_b64 exec, exec, s[8:9]
	s_nop 0
	v_add_u32_e32 v64, 0x200, v204
	v_ashrrev_i32_e32 v96, 4, v64
	v_ashrrev_i32_e32 v64, 3, v64
	v_and_b32_e32 v150, 0xffffff80, v64
	v_mul_lo_u32 v104, v96, s66
	v_add_u32_e32 v207, s28, v150
	v_and_b32_e32 v138, 63, v96
	v_lshl_add_u32 v140, v130, 2, v104
	s_and_saveexec_b64 s[8:9], s[6:7]
	s_cbranch_execz .LBB0_198
	v_or_b32_e32 v90, v207, v138
	v_mul_hi_i32 v80, v90, s55
	ds_read_b128 v[68:71], v140
	ds_read_b128 v[76:79], v140 offset:16
	v_lshrrev_b32_e32 v81, 31, v80
	v_ashrrev_i32_e32 v80, 9, v80
	v_add_u32_e32 v80, v80, v81
	v_mul_i32_i24_e32 v80, 0x900, v80
	v_sub_u32_e32 v91, v90, v80
	s_xor_b64 s[20:21], s[46:47], -1
	v_cmp_lt_i32_e32 vcc, s62, v91
	s_and_b64 s[26:27], vcc, s[20:21]
	s_waitcnt lgkmcnt(0)
	v_pk_add_f32 v[68:69], v[68:69], v[220:221]
	v_pk_add_f32 v[70:71], v[70:71], v[222:223]
	v_pk_add_f32 v[64:65], v[76:77], v[224:225]
	v_pk_add_f32 v[66:67], v[78:79], v[226:227]
	s_and_saveexec_b64 s[20:21], s[26:27]
	s_cbranch_execz .LBB0_196
	s_lshl_b64 s[26:27], s[24:25], 2
	s_add_u32 s26, s14, s26
	v_lshlrev_b32_e32 v76, 2, v132
	s_addc_u32 s27, s15, s27
	global_load_dwordx4 v[72:75], v76, s[26:27] offset:16
	global_load_dwordx4 v[80:83], v76, s[26:27]
	v_add_u32_e32 v76, v104, v76
	ds_read_b128 v[84:87], v76
	ds_read_b128 v[76:79], v76 offset:16
	v_add_u32_e32 v92, 0xffffff00, v91
	v_lshrrev_b32_e32 v92, 6, v92
	v_and_b32_e32 v91, 63, v91
	v_cndmask_b32_e64 v91, v91, v92, s[4:5]
	s_andn2_b64 vcc, exec, s[44:45]
	s_mov_b64 s[26:27], -1
	s_cbranch_vccnz .LBB0_193
	v_lshlrev_b32_e32 v160, 6, v91
	v_lshl_add_u64 v[92:93], s[18:19], 0, v[160:161]
	s_mov_b64 s[26:27], 0

;   DI void operator()(int mt, int nt, int wm, int wn, int r, int h, f32x16 (&acc)[WM][2]) const {
;     ...
;       for (int j = 0; j < 8; ++j) {
;         const int id = tid + 256 * j;
;         const int lr = id >> 4, cc = id & 15;
;         const int row = mt * (WM * 64) + (lr >> 6) * (WM * 32) + ps * 64 + (lr & 63);
;         const int col0 = nt * 128 + cc * 8;
;         if (col0 < PW) {
;           const int t = row % NTOK;
;           const int ropemode = (t >= NCTX) ? ropemode0 : 0;
;           const float4 a0 = *(const float4*)(T + lr * LD + cc * 8), a1 = *(const float4*)(T + lr * LD + cc * 8 + 4);
;           const float4 b0 = *(const float4*)(bias + col0), b1 = *(const float4*)(bias + col0 + 4);
;           float v[8] = {a0.x + b0.x, a0.y + b0.y, a0.z + b0.z, a0.w + b0.w, a1.x + b1.x, a1.y + b1.y, a1.z + b1.z, a1.w + b1.w};
.LBB0_198:
	s_or_b64 exec, exec, s[8:9]
	s_nop 0
	v_add_u32_e32 v64, 0x300, v204
	v_ashrrev_i32_e32 v97, 4, v64
	v_ashrrev_i32_e32 v64, 3, v64
	v_and_b32_e32 v171, 0xffffff80, v64
	v_mul_lo_u32 v105, v97, s66
	v_add_u32_e32 v208, s28, v171
	v_and_b32_e32 v145, 63, v97
	v_lshl_add_u32 v146, v130, 2, v105
	s_and_saveexec_b64 s[8:9], s[6:7]
	s_cbranch_execz .LBB0_207
	v_or_b32_e32 v90, v208, v145
	v_mul_hi_i32 v80, v90, s55
	ds_read_b128 v[68:71], v146
	ds_read_b128 v[76:79], v146 offset:16
	v_lshrrev_b32_e32 v81, 31, v80
	v_ashrrev_i32_e32 v80, 9, v80
	v_add_u32_e32 v80, v80, v81
	v_mul_i32_i24_e32 v80, 0x900, v80
	v_sub_u32_e32 v91, v90, v80
	s_xor_b64 s[20:21], s[46:47], -1
	v_cmp_lt_i32_e32 vcc, s62, v91
	s_and_b64 s[26:27], vcc, s[20:21]
	s_waitcnt lgkmcnt(0)
	v_pk_add_f32 v[68:69], v[68:69], v[220:221]
	v_pk_add_f32 v[70:71], v[70:71], v[222:223]
	v_pk_add_f32 v[64:65], v[76:77], v[224:225]
	v_pk_add_f32 v[66:67], v[78:79], v[226:227]
	s_and_saveexec_b64 s[20:21], s[26:27]
	s_cbranch_execz .LBB0_205
	s_lshl_b64 s[26:27], s[24:25], 2
	s_add_u32 s26, s14, s26
	v_lshlrev_b32_e32 v76, 2, v132
	s_addc_u32 s27, s15, s27
	global_load_dwordx4 v[72:75], v76, s[26:27] offset:16
	global_load_dwordx4 v[80:83], v76, s[26:27]
	v_add_u32_e32 v76, v105, v76
	ds_read_b128 v[84:87], v76
	ds_read_b128 v[76:79], v76 offset:16
	v_add_u32_e32 v92, 0xffffff00, v91
	v_lshrrev_b32_e32 v92, 6, v92
	v_and_b32_e32 v91, 63, v91
	v_cndmask_b32_e64 v91, v91, v92, s[4:5]
	s_andn2_b64 vcc, exec, s[44:45]
	s_mov_b64 s[26:27], -1
	s_cbranch_vccnz .LBB0_202
	v_lshlrev_b32_e32 v160, 6, v91
	v_lshl_add_u64 v[92:93], s[18:19], 0, v[160:161]
	s_mov_b64 s[26:27], 0

;   DI void operator()(int mt, int nt, int wm, int wn, int r, int h, f32x16 (&acc)[WM][2]) const {
;     ...
;       for (int j = 0; j < 8; ++j) {
;         const int id = tid + 256 * j;
;         const int lr = id >> 4, cc = id & 15;
;         const int row = mt * (WM * 64) + (lr >> 6) * (WM * 32) + ps * 64 + (lr & 63);
;         const int col0 = nt * 128 + cc * 8;
;         if (col0 < PW) {
;           const int t = row % NTOK;
;           const int ropemode = (t >= NCTX) ? ropemode0 : 0;
;           const float4 a0 = *(const float4*)(T + lr * LD + cc * 8), a1 = *(const float4*)(T + lr * LD + cc * 8 + 4);
;           const float4 b0 = *(const float4*)(bias + col0), b1 = *(const float4*)(bias + col0 + 4);
;           float v[8] = {a0.x + b0.x, a0.y + b0.y, a0.z + b0.z, a0.w + b0.w, a1.x + b1.x, a1.y + b1.y, a1.z + b1.z, a1.w + b1.w};
.LBB0_207:
	s_or_b64 exec, exec, s[8:9]
	s_nop 0
	v_add_u32_e32 v64, 0x400, v204
	v_ashrrev_i32_e32 v98, 4, v64
	v_ashrrev_i32_e32 v64, 3, v64
	v_and_b32_e32 v198, 0xffffff80, v64
	v_mul_lo_u32 v106, v98, s66
	v_add_u32_e32 v209, s28, v198
	v_and_b32_e32 v148, 63, v98
	v_lshl_add_u32 v149, v130, 2, v106
	s_and_saveexec_b64 s[8:9], s[6:7]
	s_cbranch_execz .LBB0_216
	v_or_b32_e32 v90, v209, v148
	v_mul_hi_i32 v80, v90, s55
	ds_read_b128 v[68:71], v149
	ds_read_b128 v[76:79], v149 offset:16
	v_lshrrev_b32_e32 v81, 31, v80
	v_ashrrev_i32_e32 v80, 9, v80
	v_add_u32_e32 v80, v80, v81
	v_mul_i32_i24_e32 v80, 0x900, v80
	v_sub_u32_e32 v91, v90, v80
	s_xor_b64 s[20:21], s[46:47], -1
	v_cmp_lt_i32_e32 vcc, s62, v91
	s_and_b64 s[26:27], vcc, s[20:21]
	s_waitcnt lgkmcnt(0)
	v_pk_add_f32 v[68:69], v[68:69], v[220:221]
	v_pk_add_f32 v[70:71], v[70:71], v[222:223]
	v_pk_add_f32 v[64:65], v[76:77], v[224:225]
	v_pk_add_f32 v[66:67], v[78:79], v[226:227]
	s_and_saveexec_b64 s[20:21], s[26:27]
	s_cbranch_execz .LBB0_214
	s_lshl_b64 s[26:27], s[24:25], 2
	s_add_u32 s26, s14, s26
	v_lshlrev_b32_e32 v76, 2, v132
	s_addc_u32 s27, s15, s27
	global_load_dwordx4 v[72:75], v76, s[26:27] offset:16
	global_load_dwordx4 v[80:83], v76, s[26:27]
	v_add_u32_e32 v76, v106, v76
	ds_read_b128 v[84:87], v76
	ds_read_b128 v[76:79], v76 offset:16
	v_add_u32_e32 v92, 0xffffff00, v91
	v_lshrrev_b32_e32 v92, 6, v92
	v_and_b32_e32 v91, 63, v91
	v_cndmask_b32_e64 v91, v91, v92, s[4:5]
	s_andn2_b64 vcc, exec, s[44:45]
	s_mov_b64 s[26:27], -1
	s_cbranch_vccnz .LBB0_211
	v_lshlrev_b32_e32 v160, 6, v91
	v_lshl_add_u64 v[92:93], s[18:19], 0, v[160:161]
	s_mov_b64 s[26:27], 0

;   DI void operator()(int mt, int nt, int wm, int wn, int r, int h, f32x16 (&acc)[WM][2]) const {
;     ...
;       for (int j = 0; j < 8; ++j) {
;         const int id = tid + 256 * j;
;         const int lr = id >> 4, cc = id & 15;
;         const int row = mt * (WM * 64) + (lr >> 6) * (WM * 32) + ps * 64 + (lr & 63);
;         const int col0 = nt * 128 + cc * 8;
;         if (col0 < PW) {
;           const int t = row % NTOK;
;           const int ropemode = (t >= NCTX) ? ropemode0 : 0;
;           const float4 a0 = *(const float4*)(T + lr * LD + cc * 8), a1 = *(const float4*)(T + lr * LD + cc * 8 + 4);
;           const float4 b0 = *(const float4*)(bias + col0), b1 = *(const float4*)(bias + col0 + 4);
;           float v[8] = {a0.x + b0.x, a0.y + b0.y, a0.z + b0.z, a0.w + b0.w, a1.x + b1.x, a1.y + b1.y, a1.z + b1.z, a1.w + b1.w};
.LBB0_216:
	s_or_b64 exec, exec, s[8:9]
	s_nop 0
	v_add_u32_e32 v64, 0x500, v204
	v_ashrrev_i32_e32 v99, 4, v64
	v_ashrrev_i32_e32 v64, 3, v64
	v_and_b32_e32 v201, 0xffffff80, v64
	v_mul_lo_u32 v107, v99, s66
	v_add_u32_e32 v210, s28, v201
	v_and_b32_e32 v151, 63, v99
	v_lshl_add_u32 v170, v130, 2, v107
	s_and_saveexec_b64 s[8:9], s[6:7]
	s_cbranch_execz .LBB0_225
	v_or_b32_e32 v90, v210, v151
	v_mul_hi_i32 v80, v90, s55
	ds_read_b128 v[68:71], v170
	ds_read_b128 v[76:79], v170 offset:16
	v_lshrrev_b32_e32 v81, 31, v80
	v_ashrrev_i32_e32 v80, 9, v80
	v_add_u32_e32 v80, v80, v81
	v_mul_i32_i24_e32 v80, 0x900, v80
	v_sub_u32_e32 v91, v90, v80
	s_xor_b64 s[20:21], s[46:47], -1
	v_cmp_lt_i32_e32 vcc, s62, v91
	s_and_b64 s[26:27], vcc, s[20:21]
	s_waitcnt lgkmcnt(0)
	v_pk_add_f32 v[68:69], v[68:69], v[220:221]
	v_pk_add_f32 v[70:71], v[70:71], v[222:223]
	v_pk_add_f32 v[64:65], v[76:77], v[224:225]
	v_pk_add_f32 v[66:67], v[78:79], v[226:227]
	s_and_saveexec_b64 s[20:21], s[26:27]
	s_cbranch_execz .LBB0_223
	s_lshl_b64 s[26:27], s[24:25], 2
	s_add_u32 s26, s14, s26
	v_lshlrev_b32_e32 v76, 2, v132
	s_addc_u32 s27, s15, s27
	global_load_dwordx4 v[72:75], v76, s[26:27] offset:16
	global_load_dwordx4 v[80:83], v76, s[26:27]
	v_add_u32_e32 v76, v107, v76
	ds_read_b128 v[84:87], v76
	ds_read_b128 v[76:79], v76 offset:16
	v_add_u32_e32 v92, 0xffffff00, v91
	v_lshrrev_b32_e32 v92, 6, v92
	v_and_b32_e32 v91, 63, v91
	v_cndmask_b32_e64 v91, v91, v92, s[4:5]
	s_andn2_b64 vcc, exec, s[44:45]
	s_mov_b64 s[26:27], -1
	s_cbranch_vccnz .LBB0_220
	v_lshlrev_b32_e32 v160, 6, v91
	v_lshl_add_u64 v[92:93], s[18:19], 0, v[160:161]
	s_mov_b64 s[26:27], 0

;   DI void operator()(int mt, int nt, int wm, int wn, int r, int h, f32x16 (&acc)[WM][2]) const {
;     ...
;       for (int j = 0; j < 8; ++j) {
;         const int id = tid + 256 * j;
;         const int lr = id >> 4, cc = id & 15;
;         const int row = mt * (WM * 64) + (lr >> 6) * (WM * 32) + ps * 64 + (lr & 63);
;         const int col0 = nt * 128 + cc * 8;
;         if (col0 < PW) {
;           const int t = row % NTOK;
;           const int ropemode = (t >= NCTX) ? ropemode0 : 0;
;           const float4 a0 = *(const float4*)(T + lr * LD + cc * 8), a1 = *(const float4*)(T + lr * LD + cc * 8 + 4);
;           const float4 b0 = *(const float4*)(bias + col0), b1 = *(const float4*)(bias + col0 + 4);
;           float v[8] = {a0.x + b0.x, a0.y + b0.y, a0.z + b0.z, a0.w + b0.w, a1.x + b1.x, a1.y + b1.y, a1.z + b1.z, a1.w + b1.w};
.LBB0_225:
	s_or_b64 exec, exec, s[8:9]
	s_nop 0
	v_add_u32_e32 v64, 0x600, v204
	v_ashrrev_i32_e32 v100, 4, v64
	v_ashrrev_i32_e32 v64, 3, v64
	v_and_b32_e32 v202, 0xffffff80, v64
	v_mul_lo_u32 v108, v100, s66
	v_add_u32_e32 v211, s28, v202
	v_and_b32_e32 v196, 63, v100
	v_lshl_add_u32 v197, v130, 2, v108
	s_and_saveexec_b64 s[8:9], s[6:7]
	s_cbranch_execz .LBB0_234
	v_or_b32_e32 v90, v211, v196
	v_mul_hi_i32 v80, v90, s55
	ds_read_b128 v[68:71], v197
	ds_read_b128 v[76:79], v197 offset:16
	v_lshrrev_b32_e32 v81, 31, v80
	v_ashrrev_i32_e32 v80, 9, v80
	v_add_u32_e32 v80, v80, v81
	v_mul_i32_i24_e32 v80, 0x900, v80
	v_sub_u32_e32 v91, v90, v80
	s_xor_b64 s[20:21], s[46:47], -1
	v_cmp_lt_i32_e32 vcc, s62, v91
	s_and_b64 s[26:27], vcc, s[20:21]
	s_waitcnt lgkmcnt(0)
	v_pk_add_f32 v[68:69], v[68:69], v[220:221]
	v_pk_add_f32 v[70:71], v[70:71], v[222:223]
	v_pk_add_f32 v[64:65], v[76:77], v[224:225]
	v_pk_add_f32 v[66:67], v[78:79], v[226:227]
	s_and_saveexec_b64 s[20:21], s[26:27]
	s_cbranch_execz .LBB0_232
	s_lshl_b64 s[26:27], s[24:25], 2
	s_add_u32 s26, s14, s26
	v_lshlrev_b32_e32 v76, 2, v132
	s_addc_u32 s27, s15, s27
	global_load_dwordx4 v[72:75], v76, s[26:27] offset:16
	global_load_dwordx4 v[80:83], v76, s[26:27]
	v_add_u32_e32 v76, v108, v76
	ds_read_b128 v[84:87], v76
	ds_read_b128 v[76:79], v76 offset:16
	v_add_u32_e32 v92, 0xffffff00, v91
	v_lshrrev_b32_e32 v92, 6, v92
	v_and_b32_e32 v91, 63, v91
	v_cndmask_b32_e64 v91, v91, v92, s[4:5]
	s_andn2_b64 vcc, exec, s[44:45]
	s_mov_b64 s[26:27], -1
	s_cbranch_vccnz .LBB0_229
	v_lshlrev_b32_e32 v160, 6, v91
	v_lshl_add_u64 v[92:93], s[18:19], 0, v[160:161]
	s_mov_b64 s[26:27], 0

;   DI void operator()(int mt, int nt, int wm, int wn, int r, int h, f32x16 (&acc)[WM][2]) const {
;     ...
;       for (int j = 0; j < 8; ++j) {
;         const int id = tid + 256 * j;
;         const int lr = id >> 4, cc = id & 15;
;         const int row = mt * (WM * 64) + (lr >> 6) * (WM * 32) + ps * 64 + (lr & 63);
;         const int col0 = nt * 128 + cc * 8;
;         if (col0 < PW) {
;           const int t = row % NTOK;
;           const int ropemode = (t >= NCTX) ? ropemode0 : 0;
;           const float4 a0 = *(const float4*)(T + lr * LD + cc * 8), a1 = *(const float4*)(T + lr * LD + cc * 8 + 4);
;           const float4 b0 = *(const float4*)(bias + col0), b1 = *(const float4*)(bias + col0 + 4);
;           float v[8] = {a0.x + b0.x, a0.y + b0.y, a0.z + b0.z, a0.w + b0.w, a1.x + b1.x, a1.y + b1.y, a1.z + b1.z, a1.w + b1.w};
.LBB0_234:
	s_or_b64 exec, exec, s[8:9]
	s_nop 0
	v_add_u32_e32 v64, 0x700, v204
	v_ashrrev_i32_e32 v101, 4, v64
	v_ashrrev_i32_e32 v64, 3, v64
	v_and_b32_e32 v203, 0xffffff80, v64
	v_mul_lo_u32 v109, v101, s66
	v_add_u32_e32 v212, s28, v203
	v_and_b32_e32 v199, 63, v101
	v_lshl_add_u32 v200, v130, 2, v109
	s_and_saveexec_b64 s[8:9], s[6:7]
	s_cbranch_execz .LBB0_243
	v_or_b32_e32 v90, v212, v199
	v_mul_hi_i32 v80, v90, s55
	ds_read_b128 v[68:71], v200
	ds_read_b128 v[76:79], v200 offset:16
	v_lshrrev_b32_e32 v81, 31, v80
	v_ashrrev_i32_e32 v80, 9, v80
	v_add_u32_e32 v80, v80, v81
	v_mul_i32_i24_e32 v80, 0x900, v80
	v_sub_u32_e32 v91, v90, v80
	s_xor_b64 s[20:21], s[46:47], -1
	v_cmp_lt_i32_e32 vcc, s62, v91
	s_and_b64 s[26:27], vcc, s[20:21]
	s_waitcnt lgkmcnt(0)
	v_pk_add_f32 v[68:69], v[68:69], v[220:221]
	v_pk_add_f32 v[70:71], v[70:71], v[222:223]
	v_pk_add_f32 v[64:65], v[76:77], v[224:225]
	v_pk_add_f32 v[66:67], v[78:79], v[226:227]
	s_and_saveexec_b64 s[20:21], s[26:27]
	s_cbranch_execz .LBB0_241
	s_lshl_b64 s[26:27], s[24:25], 2
	s_add_u32 s26, s14, s26
	v_lshlrev_b32_e32 v76, 2, v132
	s_addc_u32 s27, s15, s27
	global_load_dwordx4 v[72:75], v76, s[26:27] offset:16
	global_load_dwordx4 v[80:83], v76, s[26:27]
	v_add_u32_e32 v76, v109, v76
	ds_read_b128 v[84:87], v76
	ds_read_b128 v[76:79], v76 offset:16
	v_add_u32_e32 v92, 0xffffff00, v91
	v_lshrrev_b32_e32 v92, 6, v92
	v_and_b32_e32 v91, 63, v91
	v_cndmask_b32_e64 v91, v91, v92, s[4:5]
	s_andn2_b64 vcc, exec, s[44:45]
	s_mov_b64 s[26:27], -1
	s_cbranch_vccnz .LBB0_238
	v_lshlrev_b32_e32 v160, 6, v91
	v_lshl_add_u64 v[92:93], s[18:19], 0, v[160:161]
	s_mov_b64 s[26:27], 0

; #define RAW_BARRIER() do { asm volatile("s_waitcnt lgkmcnt(0)" ::: "memory"); __builtin_amdgcn_s_barrier(); } while (0)
;   DI void operator()(int mt, int nt, int wm, int wn, int r, int h, f32x16 (&acc)[WM][2]) const {
;     ...
;     for (int ps = 0; ps < WM / 2; ++ps) {
;       RAW_BARRIER();
; #pragma unroll
;       for (int mh = 0; mh < 2; ++mh)
; #pragma unroll
;         for (int ni = 0; ni < 2; ++ni)
; #pragma unroll
;           for (int i = 0; i < 16; ++i)
;             T[(wm * 64 + mh * 32 + (i & 3) + 8 * (i >> 2) + 4 * h) * LD + wn * 64 + ni * 32 + r] = acc[ps * 2 + mh][ni][i];
;       RAW_BARRIER();
;       const int ropemode0 = (nt < 4) ? 1 : ((nt >= 14 && nt <= 16) ? 2 : 0);
; #pragma unroll
;       for (int j = 0; j < 8; ++j) {
;         const int id = tid + 256 * j;
;         const int lr = id >> 4, cc = id & 15;
;         const int row = mt * (WM * 64) + (lr >> 6) * (WM * 32) + ps * 64 + (lr & 63);
;         const int col0 = nt * 128 + cc * 8;
;         if (col0 < PW) {
;           const int t = row % NTOK;
;           const int ropemode = (t >= NCTX) ? ropemode0 : 0;
;           const float4 a0 = *(const float4*)(T + lr * LD + cc * 8), a1 = *(const float4*)(T + lr * LD + cc * 8 + 4);
;           const float4 b0 = *(const float4*)(bias + col0), b1 = *(const float4*)(bias + col0 + 4);
;           float v[8] = {a0.x + b0.x, a0.y + b0.y, a0.z + b0.z, a0.w + b0.w, a1.x + b1.x, a1.y + b1.y, a1.z + b1.z, a1.w + b1.w};
.LBB0_281:
	s_waitcnt lgkmcnt(0)
	s_barrier
	ds_write2_b32 v133, v48, v32 offset1:32
	ds_write2_b32 v133, v49, v33 offset0:132 offset1:164
	ds_write2_b32 v112, v50, v34 offset0:8 offset1:40
	ds_write2_b32 v112, v51, v35 offset0:140 offset1:172
	ds_write2_b32 v113, v52, v36 offset0:32 offset1:64
	ds_write2_b32 v113, v53, v37 offset0:164 offset1:196
	ds_write2_b32 v114, v54, v38 offset0:40 offset1:72
	ds_write2_b32 v114, v55, v39 offset0:172 offset1:204
	ds_write2_b32 v115, v56, v40 offset0:64 offset1:96
	ds_write2_b32 v115, v57, v41 offset0:196 offset1:228
	ds_write2_b32 v116, v58, v42 offset0:72 offset1:104
	ds_write2_b32 v116, v59, v43 offset0:204 offset1:236
	ds_write2_b32 v117, v60, v44 offset0:96 offset1:128
	ds_write2_b32 v118, v61, v45 offset0:100 offset1:132
	ds_write2_b32 v119, v62, v46 offset0:104 offset1:136
	ds_write2_b32 v120, v63, v47 offset0:108 offset1:140
	ds_write2_b32 v121, v16, v0 offset0:128 offset1:160
	ds_write2_b32 v122, v17, v1 offset0:4 offset1:36
	ds_write2_b32 v122, v18, v2 offset0:136 offset1:168
	ds_write2_b32 v124, v19, v3 offset0:12 offset1:44
	ds_write2_b32 v126, v20, v4 offset0:160 offset1:192
	ds_write2_b32 v127, v21, v5 offset0:36 offset1:68
	ds_write2_b32 v127, v22, v6 offset0:168 offset1:200
	ds_write2_b32 v134, v23, v7 offset0:44 offset1:76
	ds_write2_b32 v135, v24, v8 offset0:192 offset1:224
	ds_write2_b32 v136, v25, v9 offset0:68 offset1:100
	ds_write2_b32 v136, v26, v10 offset0:200 offset1:232
	ds_write2_b32 v137, v27, v11 offset0:76 offset1:108
	ds_write2_b32 v139, v28, v12 offset0:96 offset1:128
	ds_write2_b32 v141, v29, v13 offset0:100 offset1:132
	ds_write2_b32 v142, v30, v14 offset0:104 offset1:136
	ds_write2_b32 v143, v31, v15 offset0:108 offset1:140
	s_waitcnt lgkmcnt(0)
	s_or_b32 s43, s28, 64
	v_add_u32_e32 v28, s43, v144
	s_barrier
	s_and_saveexec_b64 s[8:9], s[6:7]
	s_cbranch_execz .LBB0_290
	v_or_b32_e32 v24, v28, v110
	v_mul_hi_i32 v16, v24, s55
	ds_read_b128 v[4:7], v111
	ds_read_b128 v[12:15], v111 offset:16
	v_lshrrev_b32_e32 v17, 31, v16
	v_ashrrev_i32_e32 v16, 9, v16
	v_add_u32_e32 v16, v16, v17
	v_mul_i32_i24_e32 v16, 0x900, v16
	v_sub_u32_e32 v25, v24, v16
	s_xor_b64 s[26:27], s[46:47], -1
	v_cmp_lt_i32_e32 vcc, s62, v25
	s_and_b64 s[28:29], vcc, s[26:27]
	s_waitcnt lgkmcnt(0)
	v_pk_add_f32 v[4:5], v[4:5], v[220:221]
	v_pk_add_f32 v[6:7], v[6:7], v[222:223]
	v_pk_add_f32 v[0:1], v[12:13], v[224:225]
	v_pk_add_f32 v[2:3], v[14:15], v[226:227]
	s_and_saveexec_b64 s[26:27], s[28:29]
	s_cbranch_execz .LBB0_288
	s_lshl_b64 s[28:29], s[24:25], 2
	s_add_u32 s28, s14, s28
	v_lshlrev_b32_e32 v12, 2, v132
	s_addc_u32 s29, s15, s29
	global_load_dwordx4 v[8:11], v12, s[28:29] offset:16
	global_load_dwordx4 v[16:19], v12, s[28:29]
	v_add_u32_e32 v12, v102, v12
	ds_read_b128 v[20:23], v12
	ds_read_b128 v[12:15], v12 offset:16
	v_add_u32_e32 v26, 0xffffff00, v25
	v_lshrrev_b32_e32 v26, 6, v26
	v_and_b32_e32 v25, 63, v25
	v_cndmask_b32_e64 v25, v25, v26, s[4:5]
	s_andn2_b64 vcc, exec, s[44:45]
	s_mov_b64 s[28:29], -1
	s_cbranch_vccnz .LBB0_285
	v_lshlrev_b32_e32 v160, 6, v25
	v_lshl_add_u64 v[26:27], s[18:19], 0, v[160:161]
	s_mov_b64 s[28:29], 0

;   DI void operator()(int mt, int nt, int wm, int wn, int r, int h, f32x16 (&acc)[WM][2]) const {
;     ...
;       for (int j = 0; j < 8; ++j) {
;         const int id = tid + 256 * j;
;         const int lr = id >> 4, cc = id & 15;
;         const int row = mt * (WM * 64) + (lr >> 6) * (WM * 32) + ps * 64 + (lr & 63);
;         const int col0 = nt * 128 + cc * 8;
;         if (col0 < PW) {
;           const int t = row % NTOK;
;           const int ropemode = (t >= NCTX) ? ropemode0 : 0;
;           const float4 a0 = *(const float4*)(T + lr * LD + cc * 8), a1 = *(const float4*)(T + lr * LD + cc * 8 + 4);
;           const float4 b0 = *(const float4*)(bias + col0), b1 = *(const float4*)(bias + col0 + 4);
;           float v[8] = {a0.x + b0.x, a0.y + b0.y, a0.z + b0.z, a0.w + b0.w, a1.x + b1.x, a1.y + b1.y, a1.z + b1.z, a1.w + b1.w};
.LBB0_290:
	s_or_b64 exec, exec, s[8:9]
	v_add_u32_e32 v29, s43, v147
	s_and_saveexec_b64 s[8:9], s[6:7]
	s_cbranch_execz .LBB0_299
	v_or_b32_e32 v24, v29, v123
	v_mul_hi_i32 v16, v24, s55
	ds_read_b128 v[4:7], v125
	ds_read_b128 v[12:15], v125 offset:16
	v_lshrrev_b32_e32 v17, 31, v16
	v_ashrrev_i32_e32 v16, 9, v16
	v_add_u32_e32 v16, v16, v17
	v_mul_i32_i24_e32 v16, 0x900, v16
	v_sub_u32_e32 v25, v24, v16
	s_xor_b64 s[26:27], s[46:47], -1
	v_cmp_lt_i32_e32 vcc, s62, v25
	s_and_b64 s[28:29], vcc, s[26:27]
	s_waitcnt lgkmcnt(0)
	v_pk_add_f32 v[4:5], v[4:5], v[220:221]
	v_pk_add_f32 v[6:7], v[6:7], v[222:223]
	v_pk_add_f32 v[0:1], v[12:13], v[224:225]
	v_pk_add_f32 v[2:3], v[14:15], v[226:227]
	s_and_saveexec_b64 s[26:27], s[28:29]
	s_cbranch_execz .LBB0_297
	s_lshl_b64 s[28:29], s[24:25], 2
	s_add_u32 s28, s14, s28
	v_lshlrev_b32_e32 v12, 2, v132
	s_addc_u32 s29, s15, s29
	global_load_dwordx4 v[8:11], v12, s[28:29] offset:16
	global_load_dwordx4 v[16:19], v12, s[28:29]
	v_add_u32_e32 v12, v103, v12
	ds_read_b128 v[20:23], v12
	ds_read_b128 v[12:15], v12 offset:16
	v_add_u32_e32 v26, 0xffffff00, v25
	v_lshrrev_b32_e32 v26, 6, v26
	v_and_b32_e32 v25, 63, v25
	v_cndmask_b32_e64 v25, v25, v26, s[4:5]
	s_andn2_b64 vcc, exec, s[44:45]
	s_mov_b64 s[28:29], -1
	s_cbranch_vccnz .LBB0_294
	v_lshlrev_b32_e32 v160, 6, v25
	v_lshl_add_u64 v[26:27], s[18:19], 0, v[160:161]
	s_mov_b64 s[28:29], 0

;   DI void operator()(int mt, int nt, int wm, int wn, int r, int h, f32x16 (&acc)[WM][2]) const {
;     ...
;       for (int j = 0; j < 8; ++j) {
;         const int id = tid + 256 * j;
;         const int lr = id >> 4, cc = id & 15;
;         const int row = mt * (WM * 64) + (lr >> 6) * (WM * 32) + ps * 64 + (lr & 63);
;         const int col0 = nt * 128 + cc * 8;
;         if (col0 < PW) {
;           const int t = row % NTOK;
;           const int ropemode = (t >= NCTX) ? ropemode0 : 0;
;           const float4 a0 = *(const float4*)(T + lr * LD + cc * 8), a1 = *(const float4*)(T + lr * LD + cc * 8 + 4);
;           const float4 b0 = *(const float4*)(bias + col0), b1 = *(const float4*)(bias + col0 + 4);
;           float v[8] = {a0.x + b0.x, a0.y + b0.y, a0.z + b0.z, a0.w + b0.w, a1.x + b1.x, a1.y + b1.y, a1.z + b1.z, a1.w + b1.w};
.LBB0_299:
	s_or_b64 exec, exec, s[8:9]
	v_add_u32_e32 v30, s43, v150
	s_and_saveexec_b64 s[8:9], s[6:7]
	s_cbranch_execz .LBB0_308
	v_or_b32_e32 v24, v30, v138
	v_mul_hi_i32 v16, v24, s55
	ds_read_b128 v[4:7], v140
	ds_read_b128 v[12:15], v140 offset:16
	v_lshrrev_b32_e32 v17, 31, v16
	v_ashrrev_i32_e32 v16, 9, v16
	v_add_u32_e32 v16, v16, v17
	v_mul_i32_i24_e32 v16, 0x900, v16
	v_sub_u32_e32 v25, v24, v16
	s_xor_b64 s[26:27], s[46:47], -1
	v_cmp_lt_i32_e32 vcc, s62, v25
	s_and_b64 s[28:29], vcc, s[26:27]
	s_waitcnt lgkmcnt(0)
	v_pk_add_f32 v[4:5], v[4:5], v[220:221]
	v_pk_add_f32 v[6:7], v[6:7], v[222:223]
	v_pk_add_f32 v[0:1], v[12:13], v[224:225]
	v_pk_add_f32 v[2:3], v[14:15], v[226:227]
	s_and_saveexec_b64 s[26:27], s[28:29]
	s_cbranch_execz .LBB0_306
	s_lshl_b64 s[28:29], s[24:25], 2
	s_add_u32 s28, s14, s28
	v_lshlrev_b32_e32 v12, 2, v132
	s_addc_u32 s29, s15, s29
	global_load_dwordx4 v[8:11], v12, s[28:29] offset:16
	global_load_dwordx4 v[16:19], v12, s[28:29]
	v_add_u32_e32 v12, v104, v12
	ds_read_b128 v[20:23], v12
	ds_read_b128 v[12:15], v12 offset:16
	v_add_u32_e32 v26, 0xffffff00, v25
	v_lshrrev_b32_e32 v26, 6, v26
	v_and_b32_e32 v25, 63, v25
	v_cndmask_b32_e64 v25, v25, v26, s[4:5]
	s_andn2_b64 vcc, exec, s[44:45]
	s_mov_b64 s[28:29], -1
	s_cbranch_vccnz .LBB0_303
	v_lshlrev_b32_e32 v160, 6, v25
	v_lshl_add_u64 v[26:27], s[18:19], 0, v[160:161]
	s_mov_b64 s[28:29], 0

;   DI void operator()(int mt, int nt, int wm, int wn, int r, int h, f32x16 (&acc)[WM][2]) const {
;     ...
;       for (int j = 0; j < 8; ++j) {
;         const int id = tid + 256 * j;
;         const int lr = id >> 4, cc = id & 15;
;         const int row = mt * (WM * 64) + (lr >> 6) * (WM * 32) + ps * 64 + (lr & 63);
;         const int col0 = nt * 128 + cc * 8;
;         if (col0 < PW) {
;           const int t = row % NTOK;
;           const int ropemode = (t >= NCTX) ? ropemode0 : 0;
;           const float4 a0 = *(const float4*)(T + lr * LD + cc * 8), a1 = *(const float4*)(T + lr * LD + cc * 8 + 4);
;           const float4 b0 = *(const float4*)(bias + col0), b1 = *(const float4*)(bias + col0 + 4);
;           float v[8] = {a0.x + b0.x, a0.y + b0.y, a0.z + b0.z, a0.w + b0.w, a1.x + b1.x, a1.y + b1.y, a1.z + b1.z, a1.w + b1.w};
.LBB0_308:
	s_or_b64 exec, exec, s[8:9]
	v_add_u32_e32 v31, s43, v171
	s_and_saveexec_b64 s[8:9], s[6:7]
	s_cbranch_execz .LBB0_317
	v_or_b32_e32 v24, v31, v145
	v_mul_hi_i32 v16, v24, s55
	ds_read_b128 v[4:7], v146
	ds_read_b128 v[12:15], v146 offset:16
	v_lshrrev_b32_e32 v17, 31, v16
	v_ashrrev_i32_e32 v16, 9, v16
	v_add_u32_e32 v16, v16, v17
	v_mul_i32_i24_e32 v16, 0x900, v16
	v_sub_u32_e32 v25, v24, v16
	s_xor_b64 s[26:27], s[46:47], -1
	v_cmp_lt_i32_e32 vcc, s62, v25
	s_and_b64 s[28:29], vcc, s[26:27]
	s_waitcnt lgkmcnt(0)
	v_pk_add_f32 v[4:5], v[4:5], v[220:221]
	v_pk_add_f32 v[6:7], v[6:7], v[222:223]
	v_pk_add_f32 v[0:1], v[12:13], v[224:225]
	v_pk_add_f32 v[2:3], v[14:15], v[226:227]
	s_and_saveexec_b64 s[26:27], s[28:29]
	s_cbranch_execz .LBB0_315
	s_lshl_b64 s[28:29], s[24:25], 2
	s_add_u32 s28, s14, s28
	v_lshlrev_b32_e32 v12, 2, v132
	s_addc_u32 s29, s15, s29
	global_load_dwordx4 v[8:11], v12, s[28:29] offset:16
	global_load_dwordx4 v[16:19], v12, s[28:29]
	v_add_u32_e32 v12, v105, v12
	ds_read_b128 v[20:23], v12
	ds_read_b128 v[12:15], v12 offset:16
	v_add_u32_e32 v26, 0xffffff00, v25
	v_lshrrev_b32_e32 v26, 6, v26
	v_and_b32_e32 v25, 63, v25
	v_cndmask_b32_e64 v25, v25, v26, s[4:5]
	s_andn2_b64 vcc, exec, s[44:45]
	s_mov_b64 s[28:29], -1
	s_cbranch_vccnz .LBB0_312
	v_lshlrev_b32_e32 v160, 6, v25
	v_lshl_add_u64 v[26:27], s[18:19], 0, v[160:161]
	s_mov_b64 s[28:29], 0

;   DI void operator()(int mt, int nt, int wm, int wn, int r, int h, f32x16 (&acc)[WM][2]) const {
;     ...
;       for (int j = 0; j < 8; ++j) {
;         const int id = tid + 256 * j;
;         const int lr = id >> 4, cc = id & 15;
;         const int row = mt * (WM * 64) + (lr >> 6) * (WM * 32) + ps * 64 + (lr & 63);
;         const int col0 = nt * 128 + cc * 8;
;         if (col0 < PW) {
;           const int t = row % NTOK;
;           const int ropemode = (t >= NCTX) ? ropemode0 : 0;
;           const float4 a0 = *(const float4*)(T + lr * LD + cc * 8), a1 = *(const float4*)(T + lr * LD + cc * 8 + 4);
;           const float4 b0 = *(const float4*)(bias + col0), b1 = *(const float4*)(bias + col0 + 4);
;           float v[8] = {a0.x + b0.x, a0.y + b0.y, a0.z + b0.z, a0.w + b0.w, a1.x + b1.x, a1.y + b1.y, a1.z + b1.z, a1.w + b1.w};
.LBB0_317:
	s_or_b64 exec, exec, s[8:9]
	v_add_u32_e32 v32, s43, v198
	s_and_saveexec_b64 s[8:9], s[6:7]
	s_cbranch_execz .LBB0_326
	v_or_b32_e32 v24, v32, v148
	v_mul_hi_i32 v16, v24, s55
	ds_read_b128 v[4:7], v149
	ds_read_b128 v[12:15], v149 offset:16
	v_lshrrev_b32_e32 v17, 31, v16
	v_ashrrev_i32_e32 v16, 9, v16
	v_add_u32_e32 v16, v16, v17
	v_mul_i32_i24_e32 v16, 0x900, v16
	v_sub_u32_e32 v25, v24, v16
	s_xor_b64 s[26:27], s[46:47], -1
	v_cmp_lt_i32_e32 vcc, s62, v25
	s_and_b64 s[28:29], vcc, s[26:27]
	s_waitcnt lgkmcnt(0)
	v_pk_add_f32 v[4:5], v[4:5], v[220:221]
	v_pk_add_f32 v[6:7], v[6:7], v[222:223]
	v_pk_add_f32 v[0:1], v[12:13], v[224:225]
	v_pk_add_f32 v[2:3], v[14:15], v[226:227]
	s_and_saveexec_b64 s[26:27], s[28:29]
	s_cbranch_execz .LBB0_324
	s_lshl_b64 s[28:29], s[24:25], 2
	s_add_u32 s28, s14, s28
	v_lshlrev_b32_e32 v12, 2, v132
	s_addc_u32 s29, s15, s29
	global_load_dwordx4 v[8:11], v12, s[28:29] offset:16
	global_load_dwordx4 v[16:19], v12, s[28:29]
	v_add_u32_e32 v12, v106, v12
	ds_read_b128 v[20:23], v12
	ds_read_b128 v[12:15], v12 offset:16
	v_add_u32_e32 v26, 0xffffff00, v25
	v_lshrrev_b32_e32 v26, 6, v26
	v_and_b32_e32 v25, 63, v25
	v_cndmask_b32_e64 v25, v25, v26, s[4:5]
	s_andn2_b64 vcc, exec, s[44:45]
	s_mov_b64 s[28:29], -1
	s_cbranch_vccnz .LBB0_321
	v_lshlrev_b32_e32 v160, 6, v25
	v_lshl_add_u64 v[26:27], s[18:19], 0, v[160:161]
	s_mov_b64 s[28:29], 0

;   DI void operator()(int mt, int nt, int wm, int wn, int r, int h, f32x16 (&acc)[WM][2]) const {
;     ...
;       for (int j = 0; j < 8; ++j) {
;         const int id = tid + 256 * j;
;         const int lr = id >> 4, cc = id & 15;
;         const int row = mt * (WM * 64) + (lr >> 6) * (WM * 32) + ps * 64 + (lr & 63);
;         const int col0 = nt * 128 + cc * 8;
;         if (col0 < PW) {
;           const int t = row % NTOK;
;           const int ropemode = (t >= NCTX) ? ropemode0 : 0;
;           const float4 a0 = *(const float4*)(T + lr * LD + cc * 8), a1 = *(const float4*)(T + lr * LD + cc * 8 + 4);
;           const float4 b0 = *(const float4*)(bias + col0), b1 = *(const float4*)(bias + col0 + 4);
;           float v[8] = {a0.x + b0.x, a0.y + b0.y, a0.z + b0.z, a0.w + b0.w, a1.x + b1.x, a1.y + b1.y, a1.z + b1.z, a1.w + b1.w};
.LBB0_326:
	s_or_b64 exec, exec, s[8:9]
	v_add_u32_e32 v33, s43, v201
	s_and_saveexec_b64 s[8:9], s[6:7]
	s_cbranch_execz .LBB0_335
	v_or_b32_e32 v24, v33, v151
	v_mul_hi_i32 v16, v24, s55
	ds_read_b128 v[4:7], v170
	ds_read_b128 v[12:15], v170 offset:16
	v_lshrrev_b32_e32 v17, 31, v16
	v_ashrrev_i32_e32 v16, 9, v16
	v_add_u32_e32 v16, v16, v17
	v_mul_i32_i24_e32 v16, 0x900, v16
	v_sub_u32_e32 v25, v24, v16
	s_xor_b64 s[26:27], s[46:47], -1
	v_cmp_lt_i32_e32 vcc, s62, v25
	s_and_b64 s[28:29], vcc, s[26:27]
	s_waitcnt lgkmcnt(0)
	v_pk_add_f32 v[4:5], v[4:5], v[220:221]
	v_pk_add_f32 v[6:7], v[6:7], v[222:223]
	v_pk_add_f32 v[0:1], v[12:13], v[224:225]
	v_pk_add_f32 v[2:3], v[14:15], v[226:227]
	s_and_saveexec_b64 s[26:27], s[28:29]
	s_cbranch_execz .LBB0_333
	s_lshl_b64 s[28:29], s[24:25], 2
	s_add_u32 s28, s14, s28
	v_lshlrev_b32_e32 v12, 2, v132
	s_addc_u32 s29, s15, s29
	global_load_dwordx4 v[8:11], v12, s[28:29] offset:16
	global_load_dwordx4 v[16:19], v12, s[28:29]
	v_add_u32_e32 v12, v107, v12
	ds_read_b128 v[20:23], v12
	ds_read_b128 v[12:15], v12 offset:16
	v_add_u32_e32 v26, 0xffffff00, v25
	v_lshrrev_b32_e32 v26, 6, v26
	v_and_b32_e32 v25, 63, v25
	v_cndmask_b32_e64 v25, v25, v26, s[4:5]
	s_andn2_b64 vcc, exec, s[44:45]
	s_mov_b64 s[28:29], -1
	s_cbranch_vccnz .LBB0_330
	v_lshlrev_b32_e32 v160, 6, v25
	v_lshl_add_u64 v[26:27], s[18:19], 0, v[160:161]
	s_mov_b64 s[28:29], 0

;   DI void operator()(int mt, int nt, int wm, int wn, int r, int h, f32x16 (&acc)[WM][2]) const {
;     ...
;       for (int j = 0; j < 8; ++j) {
;         const int id = tid + 256 * j;
;         const int lr = id >> 4, cc = id & 15;
;         const int row = mt * (WM * 64) + (lr >> 6) * (WM * 32) + ps * 64 + (lr & 63);
;         const int col0 = nt * 128 + cc * 8;
;         if (col0 < PW) {
;           const int t = row % NTOK;
;           const int ropemode = (t >= NCTX) ? ropemode0 : 0;
;           const float4 a0 = *(const float4*)(T + lr * LD + cc * 8), a1 = *(const float4*)(T + lr * LD + cc * 8 + 4);
;           const float4 b0 = *(const float4*)(bias + col0), b1 = *(const float4*)(bias + col0 + 4);
;           float v[8] = {a0.x + b0.x, a0.y + b0.y, a0.z + b0.z, a0.w + b0.w, a1.x + b1.x, a1.y + b1.y, a1.z + b1.z, a1.w + b1.w};
.LBB0_335:
	s_or_b64 exec, exec, s[8:9]
	v_add_u32_e32 v34, s43, v202
	s_and_saveexec_b64 s[8:9], s[6:7]
	s_cbranch_execz .LBB0_344
	v_or_b32_e32 v24, v34, v196
	v_mul_hi_i32 v16, v24, s55
	ds_read_b128 v[4:7], v197
	ds_read_b128 v[12:15], v197 offset:16
	v_lshrrev_b32_e32 v17, 31, v16
	v_ashrrev_i32_e32 v16, 9, v16
	v_add_u32_e32 v16, v16, v17
	v_mul_i32_i24_e32 v16, 0x900, v16
	v_sub_u32_e32 v25, v24, v16
	s_xor_b64 s[26:27], s[46:47], -1
	v_cmp_lt_i32_e32 vcc, s62, v25
	s_and_b64 s[28:29], vcc, s[26:27]
	s_waitcnt lgkmcnt(0)
	v_pk_add_f32 v[4:5], v[4:5], v[220:221]
	v_pk_add_f32 v[6:7], v[6:7], v[222:223]
	v_pk_add_f32 v[0:1], v[12:13], v[224:225]
	v_pk_add_f32 v[2:3], v[14:15], v[226:227]
	s_and_saveexec_b64 s[26:27], s[28:29]
	s_cbranch_execz .LBB0_342
	s_lshl_b64 s[28:29], s[24:25], 2
	s_add_u32 s28, s14, s28
	v_lshlrev_b32_e32 v12, 2, v132
	s_addc_u32 s29, s15, s29
	global_load_dwordx4 v[8:11], v12, s[28:29] offset:16
	global_load_dwordx4 v[16:19], v12, s[28:29]
	v_add_u32_e32 v12, v108, v12
	ds_read_b128 v[20:23], v12
	ds_read_b128 v[12:15], v12 offset:16
	v_add_u32_e32 v26, 0xffffff00, v25
	v_lshrrev_b32_e32 v26, 6, v26
	v_and_b32_e32 v25, 63, v25
	v_cndmask_b32_e64 v25, v25, v26, s[4:5]
	s_andn2_b64 vcc, exec, s[44:45]
	s_mov_b64 s[28:29], -1
	s_cbranch_vccnz .LBB0_339
	v_lshlrev_b32_e32 v160, 6, v25
	v_lshl_add_u64 v[26:27], s[18:19], 0, v[160:161]
	s_mov_b64 s[28:29], 0

;   DI void operator()(int mt, int nt, int wm, int wn, int r, int h, f32x16 (&acc)[WM][2]) const {
;     ...
;       for (int j = 0; j < 8; ++j) {
;         const int id = tid + 256 * j;
;         const int lr = id >> 4, cc = id & 15;
;         const int row = mt * (WM * 64) + (lr >> 6) * (WM * 32) + ps * 64 + (lr & 63);
;         const int col0 = nt * 128 + cc * 8;
;         if (col0 < PW) {
;           const int t = row % NTOK;
;           const int ropemode = (t >= NCTX) ? ropemode0 : 0;
;           const float4 a0 = *(const float4*)(T + lr * LD + cc * 8), a1 = *(const float4*)(T + lr * LD + cc * 8 + 4);
;           const float4 b0 = *(const float4*)(bias + col0), b1 = *(const float4*)(bias + col0 + 4);
;           float v[8] = {a0.x + b0.x, a0.y + b0.y, a0.z + b0.z, a0.w + b0.w, a1.x + b1.x, a1.y + b1.y, a1.z + b1.z, a1.w + b1.w};
.LBB0_344:
	s_or_b64 exec, exec, s[8:9]
	v_add_u32_e32 v35, s43, v203
	s_and_saveexec_b64 s[8:9], s[6:7]
	s_cbranch_execz .LBB0_353
	v_or_b32_e32 v24, v35, v199
	v_mul_hi_i32 v16, v24, s55
	ds_read_b128 v[4:7], v200
	ds_read_b128 v[12:15], v200 offset:16
	v_lshrrev_b32_e32 v17, 31, v16
	v_ashrrev_i32_e32 v16, 9, v16
	v_add_u32_e32 v16, v16, v17
	v_mul_i32_i24_e32 v16, 0x900, v16
	v_sub_u32_e32 v25, v24, v16
	s_xor_b64 s[6:7], s[46:47], -1
	v_cmp_lt_i32_e32 vcc, s62, v25
	s_and_b64 s[26:27], vcc, s[6:7]
	s_waitcnt lgkmcnt(0)
	v_pk_add_f32 v[4:5], v[4:5], v[220:221]
	v_pk_add_f32 v[6:7], v[6:7], v[222:223]
	v_pk_add_f32 v[0:1], v[12:13], v[224:225]
	v_pk_add_f32 v[2:3], v[14:15], v[226:227]
	s_and_saveexec_b64 s[6:7], s[26:27]
	s_cbranch_execz .LBB0_351
	s_lshl_b64 s[24:25], s[24:25], 2
	s_add_u32 s24, s14, s24
	v_lshlrev_b32_e32 v12, 2, v132
	s_addc_u32 s25, s15, s25
	global_load_dwordx4 v[8:11], v12, s[24:25] offset:16
	global_load_dwordx4 v[16:19], v12, s[24:25]
	v_add_u32_e32 v12, v109, v12
	ds_read_b128 v[20:23], v12
	ds_read_b128 v[12:15], v12 offset:16
	v_add_u32_e32 v26, 0xffffff00, v25
	v_lshrrev_b32_e32 v26, 6, v26
	v_and_b32_e32 v25, 63, v25
	v_cndmask_b32_e64 v25, v25, v26, s[4:5]
	s_andn2_b64 vcc, exec, s[44:45]
	s_mov_b64 s[4:5], -1
	s_cbranch_vccnz .LBB0_348
	v_lshlrev_b32_e32 v160, 6, v25
	v_lshl_add_u64 v[26:27], s[18:19], 0, v[160:161]
	s_mov_b64 s[4:5], 0

; template <int MODE>
; DI void attn_mfma(const Params& p, int l, int b, int hd, int qb, unsigned char* smem) {
;     ...
;   const int tid = ltid_w(p.wave), lane = tid & 63, wv = tid >> 6, r = lane & 31, h2 = lane >> 5;
;   const int mp = MODE ? 0 : (wv >> 1);
;   const bf16_t* P = (const bf16_t*)(p.ws + WS_P);
;   bf16_t* MIX = (bf16_t*)(p.ws + WS_HM);
;   const int kvh = MODE ? (hd >> 1) : hd;
;   const bf16_t* VT = MODE ? (const bf16_t*)(p.ws + WS_VTC) + ((size_t)(b * 2 + kvh) * 64) * NTOK : (const bf16_t*)(p.ws + WS_VTA) + ((size_t)(b * 4 + hd) * 64) * NTOK;
;   const int qcol = MODE ? C_Q + hd * 64 : A_Q + hd * 64;
;   const int kcol = MODE ? C_K + kvh * 64 : A_K + hd * 64;
;   unsigned char* sK = smem;
;   unsigned char* sV = smem + 8192;
;   const int tq = qb * QPB + (MODE ? wv : (wv & 1)) * 32 + r;
;   const size_t qrow = (size_t)b * NTOK + tq;
;   bf16x8 qf[KS];
; #pragma unroll
;   for (int ks = 0; ks < KS; ++ks) qf[ks] = *(const bf16x8*)(P + qrow * PW + qcol + (2 * (mp * 2 + ks) + h2) * 8);
;   const bool isctx = qb * QPB < NCTX;
;   int ntiles, band_lo = 0;
;   if (MODE == 0) ntiles = isctx ? 4 : 36;
;   else {
;     if (isctx) ntiles = 4;
;     else { const int i0 = qb * QPB - NCTX; int lo = i0 - 128; if (lo < 0) lo = 0; int hi = i0 + 256; if (hi > NLAT) hi = NLAT; band_lo = lo; ntiles = 4 + (hi - lo) / 64; }
;   }
;   const float cexp = (MODE ? 0.125f : 0.17677669529663687f) * 1.4426950408889634f;
;   float mrun = MODE ? p.sw_sink[l * 4 + hd] * 1.4426950408889634f : -1e30f;
;   float lsum = (MODE && h2 == 0) ? 1.f : 0.f;
;   f32x16 O[2];
; #pragma unroll
;   for (int vt = 0; vt < 2; ++vt)
; #pragma unroll
;     for (int i = 0; i < 16; ++i) O[vt][i] = 0.f;
;   const int lrow = tid >> 3, lc = tid & 7;
;   auto tile_base = [&](int j) -> int { return (MODE == 0 || j < 4) ? j * 64 : NCTX + band_lo + (j - 4) * 64; };
;   uint4 gk00, gk01, gk10, gk11, gv00, gv01, gv10, gv11;
;     ...
;   ATT_LOAD(tile_base(0), gk00, gk01, gv00, gv01);
;   ATT_LOAD(tile_base(1), gk10, gk11, gv10, gv11);
; DI void ph_mixers1(const Params& p_in, int l, unsigned char* smem, volatile lds_int* slot) {
;     ...
;     } else if (it < 1216) { const int r = it - 64; const int qb = r % 36, bh = r / 36; if (!(l == 1 && qb < 4)) attn_mfma<0>(p, l, bh >> 2, bh & 3, qb, smem); }
.LBB0_575:
	s_andn2_b64 vcc, exec, s[0:1]
	s_cbranch_vccnz .LBB0_591
	s_add_i32 s0, s46, 0xffc0
	s_and_b32 s8, s0, 0xffff
	s_mul_i32 s1, s8, 0xe38f
	s_lshr_b32 s5, s1, 21
	s_mul_i32 s1, s5, 36
	s_sub_i32 s2, s0, s1
	s_and_b32 s0, s2, 0xffff
	s_cmp_lt_u32 s0, 4
	v_readlane_b32 s6, v254, 12
	s_cselect_b64 s[0:1], -1, 0
	v_readlane_b32 s7, v254, 13
	s_and_b64 s[6:7], s[6:7], s[0:1]
	s_and_b64 vcc, exec, s[6:7]
	s_cbranch_vccnz .LBB0_591
	s_and_b32 s4, 0xffff, s5
	s_lshr_b32 s9, s4, 2
	s_and_b32 s6, s4, 3
	v_readlane_b32 s4, v253, 39
	s_add_u32 s10, s40, 0x41c6000
	v_mbcnt_lo_u32_b32 v6, -1, 0
	v_mbcnt_hi_u32_b32 v6, -1, v6
	s_addc_u32 s11, s41, 0
	v_or_b32_e32 v196, s4, v6
	s_lshl_b32 s4, s9, 8
	s_lshl_b32 s7, s6, 6
	s_or_b32 s4, s7, s4
	s_mulk_i32 s4, 0x1200
	s_add_u32 s4, s40, s4
	s_addc_u32 s13, s41, 0
	s_add_u32 s12, s4, 0xef06000
	s_addc_u32 s13, s13, 0
	s_lshl_b32 s2, s2, 6
	s_and_b32 s2, s2, 0xffc0
	v_lshrrev_b32_e32 v0, 1, v196
	s_mul_i32 s14, s9, 0x900
	v_and_b32_e32 v198, 31, v6
	v_and_b32_e32 v199, 32, v0
	s_add_i32 s2, s14, s2
	v_bfe_u32 v171, v6, 5, 1
	v_or3_b32 v165, v198, s2, v199
	v_ashrrev_i32_e32 v197, 7, v196
	v_mul_lo_u32 v160, v165, s33
	v_lshlrev_b32_e32 v164, 3, v171
	v_lshl_add_u64 v[166:167], s[10:11], 0, v[160:161]
	s_lshl_b32 s2, s6, 7
	v_lshl_or_b32 v2, v197, 5, v164
	v_lshl_add_u64 v[0:1], v[166:167], 0, s[2:3]
	v_ashrrev_i32_e32 v3, 31, v2
	v_lshl_add_u64 v[0:1], v[2:3], 1, v[0:1]
	v_ashrrev_i32_e32 v8, 3, v196
	s_waitcnt vmcnt(0)
	global_load_dwordx4 v[96:99], v[0:1], off
	global_load_dwordx4 v[100:103], v[0:1], off offset:32
	v_add_u32_e32 v7, s14, v8
	v_mov_b64_e32 v[0:1], s[10:11]
	v_lshlrev_b32_e32 v9, 4, v6
	s_and_b64 s[0:1], s[0:1], exec
	v_mad_i64_i32 v[2:3], s[0:1], v7, s33, v[0:1]
	v_and_b32_e32 v160, 0x70, v9
	s_cselect_b32 s4, 4, 36
	v_lshl_add_u64 v[4:5], v[2:3], 0, s[2:3]
	v_lshl_add_u64 v[2:3], v[2:3], 0, v[160:161]
	s_or_b32 s0, s2, 0x200
	s_mov_b32 s1, s3
	v_lshl_add_u64 v[2:3], v[2:3], 0, s[0:1]
	s_mov_b32 s14, 0x44000
	v_add_co_u32_e32 v2, vcc, s14, v2
	v_lshl_add_u64 v[4:5], v[4:5], 0, v[160:161]
	s_nop 0
	v_addc_co_u32_e32 v3, vcc, 0, v3, vcc
	global_load_dwordx4 v[104:107], v[4:5], off offset:512
	global_load_dwordx4 v[108:111], v[2:3], off offset:1024
	v_mov_b64_e32 v[2:3], s[12:13]
	v_add_u32_e32 v6, 32, v8
	v_mad_i64_i32 v[4:5], s[10:11], v8, s67, v[2:3]
	v_mad_i64_i32 v[2:3], s[10:11], v6, s67, v[2:3]
	v_add_u32_e32 v6, 64, v7
	v_mad_i64_i32 v[0:1], s[10:11], v6, s33, v[0:1]
	v_lshl_add_u64 v[6:7], v[0:1], 0, s[2:3]
	v_lshl_add_u64 v[0:1], v[0:1], 0, v[160:161]
	v_lshl_add_u64 v[0:1], v[0:1], 0, s[0:1]
	v_lshl_add_u64 v[6:7], v[6:7], 0, v[160:161]
	v_add_co_u32_e32 v0, vcc, s14, v0
	v_lshl_add_u64 v[4:5], v[4:5], 0, v[160:161]
	v_lshl_add_u64 v[2:3], v[2:3], 0, v[160:161]
	v_addc_co_u32_e32 v1, vcc, 0, v1, vcc
	global_load_dwordx4 v[112:115], v[6:7], off offset:512
	global_load_dwordx4 v[116:119], v[0:1], off offset:1024
	global_load_dwordx4 v[120:123], v[4:5], off
	global_load_dwordx4 v[124:127], v[4:5], off offset:128
	global_load_dwordx4 v[128:131], v[2:3], off
	global_load_dwordx4 v[132:135], v[2:3], off offset:128
	s_movk_i32 s0, 0x70
	v_bitop3_b32 v0, v196, s0, v9 bitop3:0x48
	s_movk_i32 s0, 0x88
	v_mul_lo_u32 v2, v8, s0
	s_mul_i32 s0, s9, 0x90000
	s_mul_i32 s1, s6, 0x24000
	s_add_i32 s0, s0, s1
	v_lshlrev_b32_e32 v1, 2, v197
	v_bfe_u32 v4, v196, 1, 3
	s_lshl_b32 s0, s0, 1
	v_lshl_or_b32 v141, v8, 7, v0
	v_lshlrev_b32_e32 v0, 7, v198
	v_or_b32_e32 v3, v1, v171
	v_bitop3_b32 v1, v1, v4, v171 bitop3:0x36
	s_add_u32 s0, s40, s0
	v_lshl_add_u32 v142, v1, 4, v0
	v_bitop3_b32 v1, v3, v4, 2 bitop3:0x36
	s_addc_u32 s1, s41, 0
	v_lshl_add_u32 v143, v1, 4, v0
	v_mov_b64_e32 v[0:1], s[0:1]
	s_and_b32 s5, s5, 3
	v_mbcnt_hi_u32_b32 v5, -1, v185
	v_mad_i64_i32 v[136:137], s[0:1], v8, s67, v[0:1]
	s_lshl_b32 s5, s5, 7
	v_and_b32_e32 v7, 64, v5
	s_mul_hi_u32 s0, s8, 0x1c71c72
	s_add_u32 s5, s40, s5
	v_xor_b32_e32 v6, 32, v5
	v_add_u32_e32 v7, 64, v7
	s_mul_hi_u32 s1, s0, 0x1332000
	s_mul_i32 s0, s0, 0x1332000
	s_addc_u32 s8, s41, 0
	v_cmp_lt_i32_e32 vcc, v6, v7
	s_add_u32 s0, s5, s0
	s_addc_u32 s1, s8, s1
	v_cndmask_b32_e32 v5, v5, v6, vcc
	v_lshlrev_b32_e32 v170, 2, v5
	v_mul_u32_u24_e32 v5, 0x88, v198
	v_mov_b64_e32 v[0:1], s[0:1]
	v_mov_b32_e32 v200, 0
	s_mov_b32 s2, 0
	v_mad_i64_i32 v[138:139], s[0:1], v8, s33, v[0:1]
	v_mov_b32_e32 v140, 0xf149f2ca
	v_add_u32_e32 v144, v2, v160
	v_add_u32_e32 v145, v164, v5
	v_add_u32_e32 v236, 0x2000, v145
	v_add_u32_e32 v237, 0x3000, v145
	v_add_u32_e32 v238, 0x6000, v145
	v_add_u32_e32 v239, 0x7000, v145
	v_mov_b32_e32 v16, 0
	v_mov_b32_e32 v17, v200
	v_mov_b32_e32 v18, v200
	v_mov_b32_e32 v19, v200
	v_mov_b32_e32 v20, v200
	v_mov_b32_e32 v21, v200
	v_mov_b32_e32 v22, v200
	v_mov_b32_e32 v23, v200
	v_mov_b32_e32 v24, v200
	v_mov_b32_e32 v25, v200
	v_mov_b32_e32 v26, v200
	v_mov_b32_e32 v27, v200
	v_mov_b32_e32 v28, v200
	v_mov_b32_e32 v29, v200
	v_mov_b32_e32 v30, v200
	v_mov_b32_e32 v31, v200
	v_mov_b32_e32 v0, v200
	v_mov_b32_e32 v1, v200
	v_mov_b32_e32 v2, v200
	v_mov_b32_e32 v3, v200
	v_mov_b32_e32 v4, v200
	v_mov_b32_e32 v5, v200
	v_mov_b32_e32 v6, v200
	v_mov_b32_e32 v7, v200
	v_mov_b32_e32 v8, v200
	v_mov_b32_e32 v9, v200
	v_mov_b32_e32 v10, v200
	v_mov_b32_e32 v11, v200
	v_mov_b32_e32 v12, v200
	v_mov_b32_e32 v13, v200
	v_mov_b32_e32 v14, v200
	v_mov_b32_e32 v15, v200
	s_branch .LBB0_580

; DI unsigned pk2(float a, float b) { hwf32x2 f = {a, b}; hwbf16x2 r = __builtin_convertvector(f, hwbf16x2); return __builtin_bit_cast(unsigned, r); }
; #define MFMA32(a, b, c) __builtin_amdgcn_mfma_f32_32x32x16_bf16((a), (b), (c), 0, 0, 0)
; template <int MODE>
; DI void attn_mfma(const Params& p, int l, int b, int hd, int qb, unsigned char* smem) {
;     ...
;     const f32x2 c2 = {cexp, cexp}, m2 = {mrun, mrun};
;     f32x2 ps2 = {0.f, 0.f};
;     unsigned pk[2][8];
; #pragma unroll
;     for (int mt = 0; mt < 2; ++mt)
; #pragma unroll
;       for (int i = 0; i < 8; ++i) {
;         f32x2 z = {S[mt][2 * i], S[mt][2 * i + 1]};
;         z = z * c2 - m2;
;         f32x2 pv = {__builtin_amdgcn_exp2f(z.x), __builtin_amdgcn_exp2f(z.y)};
;         ps2 = ps2 + pv;
;         pk[mt][i] = pk2(pv.x, pv.y);
;       }
;     lsum += ps2.x + ps2.y;
; #pragma unroll
;     for (int mt = 0; mt < 2; ++mt)
; #pragma unroll
;       for (int s = 0; s < 2; ++s) {
;         const uint4 pu = make_uint4(pk[mt][4 * s], pk[mt][4 * s + 1], pk[mt][4 * s + 2], pk[mt][4 * s + 3]);
;         const bf16x8 pf = __builtin_bit_cast(bf16x8, pu);
; #pragma unroll
;         for (int vt = 0; vt < 2; ++vt) {
;           const unsigned char* bp = sVc + (vt * 32 + r) * 136 + (mt * 32 + 16 * s + 4 * h2) * 2;
;           const uint2 lo = *(const uint2*)(bp);
;           const uint2 hi = *(const uint2*)(bp + 16);
;           const uint4 u = make_uint4(lo.x, lo.y, hi.x, hi.y);
;           O[vt] = MFMA32(__builtin_bit_cast(bf16x8, u), pf, O[vt]);
;         }
;       }
.LBB0_579:
	ds_read2_b64 v[204:207], v238 offset0:64 offset1:66
	ds_read2_b64 v[208:211], v239 offset0:96 offset1:98
	ds_read2_b64 v[212:215], v238 offset0:68 offset1:70
	ds_read2_b64 v[216:219], v239 offset0:100 offset1:102
	ds_read2_b64 v[220:223], v238 offset0:72 offset1:74
	ds_read2_b64 v[224:227], v239 offset0:104 offset1:106
	ds_read2_b64 v[228:231], v238 offset0:76 offset1:78
	ds_read2_b64 v[232:235], v239 offset0:108 offset1:110
	v_mov_b32_e32 v65, v140
	v_fma_f32 v48, v48, s8, -v64
	v_fma_f32 v49, v49, s8, -v65
	v_fma_f32 v50, v50, s8, -v64
	v_fma_f32 v51, v51, s8, -v65
	v_exp_f32_e32 v48, v48
	v_exp_f32_e32 v49, v49
	v_exp_f32_e32 v50, v50
	v_exp_f32_e32 v51, v51
	v_fma_f32 v54, v54, s8, -v64
	v_fma_f32 v55, v55, s8, -v65
	v_add_f32_e64 v68, v48, 0
	v_add_f32_e64 v69, v49, 0
	v_cvt_pk_bf16_f32 v48, v48, v49
	v_add_f32_e64 v68, v50, v68
	v_add_f32_e64 v69, v51, v69
	v_cvt_pk_bf16_f32 v49, v50, v51
	v_fma_f32 v50, v52, s8, -v64
	v_fma_f32 v51, v53, s8, -v65
	v_exp_f32_e32 v54, v54
	v_exp_f32_e32 v50, v50
	v_exp_f32_e32 v51, v51
	v_exp_f32_e32 v55, v55
	v_fma_f32 v32, v32, s8, -v64
	v_fma_f32 v33, v33, s8, -v65
	s_and_b64 vcc, exec, s[0:1]
	v_add_f32_e64 v52, v50, v68
	v_add_f32_e64 v53, v51, v69
	v_cvt_pk_bf16_f32 v50, v50, v51
	v_add_f32_e64 v52, v54, v52
	v_add_f32_e64 v53, v55, v53
	v_cvt_pk_bf16_f32 v51, v54, v55
	v_fma_f32 v54, v56, s8, -v64
	v_fma_f32 v55, v57, s8, -v65
	v_exp_f32_e32 v32, v32
	v_exp_f32_e32 v54, v54
	v_exp_f32_e32 v55, v55
	v_exp_f32_e32 v33, v33
	v_add_f32_e64 v52, v54, v52
	v_add_f32_e64 v53, v55, v53
	v_cvt_pk_bf16_f32 v56, v54, v55
	v_fma_f32 v54, v58, s8, -v64
	v_fma_f32 v55, v59, s8, -v65
	s_nop 0
	v_exp_f32_e32 v54, v54
	v_exp_f32_e32 v55, v55
	s_nop 0
	v_add_f32_e64 v52, v54, v52
	v_add_f32_e64 v53, v55, v53
	v_cvt_pk_bf16_f32 v57, v54, v55
	v_fma_f32 v54, v60, s8, -v64
	v_fma_f32 v55, v61, s8, -v65
	s_nop 0
	v_exp_f32_e32 v54, v54
	v_exp_f32_e32 v55, v55
	s_nop 0
	v_add_f32_e64 v52, v54, v52
	v_add_f32_e64 v53, v55, v53
	v_cvt_pk_bf16_f32 v58, v54, v55
	v_fma_f32 v54, v62, s8, -v64
	v_fma_f32 v55, v63, s8, -v65
	s_nop 0
	v_exp_f32_e32 v54, v54
	v_exp_f32_e32 v55, v55
	s_nop 0
	v_add_f32_e64 v52, v54, v52
	v_add_f32_e64 v53, v55, v53
	v_cvt_pk_bf16_f32 v59, v54, v55
	v_add_f32_e64 v54, v32, v52
	v_add_f32_e64 v55, v33, v53
	v_cvt_pk_bf16_f32 v52, v32, v33
	v_fma_f32 v32, v34, s8, -v64
	v_fma_f32 v33, v35, s8, -v65
	s_nop 0
	v_exp_f32_e32 v32, v32
	v_exp_f32_e32 v33, v33
	s_nop 0
	v_add_f32_e64 v34, v32, v54
	v_add_f32_e64 v35, v33, v55
	v_cvt_pk_bf16_f32 v53, v32, v33
	v_fma_f32 v32, v36, s8, -v64
	v_fma_f32 v33, v37, s8, -v65
	v_fma_f32 v36, v42, s8, -v64
	v_fma_f32 v37, v43, s8, -v65
	v_exp_f32_e32 v32, v32
	v_exp_f32_e32 v33, v33
	v_exp_f32_e32 v36, v36
	v_exp_f32_e32 v37, v37
	v_add_f32_e64 v34, v32, v34
	v_add_f32_e64 v35, v33, v35
	v_cvt_pk_bf16_f32 v54, v32, v33
	v_fma_f32 v32, v38, s8, -v64
	v_fma_f32 v33, v39, s8, -v65
	s_nop 0
	v_exp_f32_e32 v32, v32
	v_exp_f32_e32 v33, v33
	s_nop 0
	v_add_f32_e64 v34, v32, v34
	v_add_f32_e64 v35, v33, v35
	v_cvt_pk_bf16_f32 v55, v32, v33
	v_fma_f32 v32, v40, s8, -v64
	v_fma_f32 v33, v41, s8, -v65
	s_nop 0
	v_exp_f32_e32 v32, v32
	v_exp_f32_e32 v33, v33
	s_nop 0
	v_add_f32_e64 v34, v32, v34
	v_add_f32_e64 v35, v33, v35
	v_cvt_pk_bf16_f32 v32, v32, v33
	v_add_f32_e64 v34, v36, v34
	v_add_f32_e64 v35, v37, v35
	v_cvt_pk_bf16_f32 v33, v36, v37
	v_fma_f32 v36, v44, s8, -v64
	v_fma_f32 v37, v45, s8, -v65
	s_nop 0
	v_exp_f32_e32 v36, v36
	v_exp_f32_e32 v37, v37
	s_nop 0
	v_add_f32_e64 v38, v36, v34
	v_add_f32_e64 v39, v37, v35
	v_cvt_pk_bf16_f32 v34, v36, v37
	v_fma_f32 v36, v46, s8, -v64
	v_fma_f32 v37, v47, s8, -v65
	s_nop 0
	v_exp_f32_e32 v40, v36
	v_exp_f32_e32 v41, v37
	s_mov_b64 s[8:9], 0x100
	v_lshl_add_u64 v[136:137], v[136:137], 0, s[8:9]
	v_add_f32_e64 v36, v40, v38
	v_add_f32_e64 v37, v41, v39
	v_cvt_pk_bf16_f32 v35, v40, v41
	s_mov_b64 s[8:9], 0x111000
	v_lshl_add_u64 v[138:139], v[138:139], 0, s[8:9]
	s_waitcnt lgkmcnt(0)
	v_mfma_f32_32x32x16_bf16 v[16:31], v[204:207], v[48:51], v[16:31]
	v_mfma_f32_32x32x16_bf16 v[0:15], v[208:211], v[48:51], v[0:15]
	v_mfma_f32_32x32x16_bf16 v[16:31], v[212:215], v[56:59], v[16:31]
	v_mfma_f32_32x32x16_bf16 v[0:15], v[216:219], v[56:59], v[0:15]
	v_mfma_f32_32x32x16_bf16 v[16:31], v[220:223], v[52:55], v[16:31]
	v_mfma_f32_32x32x16_bf16 v[0:15], v[224:227], v[52:55], v[0:15]
	v_mfma_f32_32x32x16_bf16 v[16:31], v[228:231], v[32:35], v[16:31]
	v_mfma_f32_32x32x16_bf16 v[0:15], v[232:235], v[32:35], v[0:15]
	v_add_f32_e32 v32, v36, v37
	v_add_f32_e32 v200, v66, v32
	s_cbranch_vccnz .LBB0_586
; template <int MODE>
; DI void attn_mfma(const Params& p, int l, int b, int hd, int qb, unsigned char* smem) {
;     ...
;   for (int j = 0; j < ntiles; j += 2) {
;     __syncthreads();
;     ATT_STORE(0, gk00, gk01, gv00, gv01);
;     ATT_STORE(1, gk10, gk11, gv10, gv11);
;     __syncthreads();
;     if (j + 2 < ntiles) {
;       ATT_LOAD(tile_base(j + 2), gk00, gk01, gv00, gv01);
;       ATT_LOAD(tile_base(j + 3), gk10, gk11, gv10, gv11);
;     }
;     f32x16 SA0, SA1, SB0, SB1;
; #pragma unroll
;     for (int i = 0; i < 16; ++i) { SA0[i] = 0.f; SA1[i] = 0.f; SB0[i] = 0.f; SB1[i] = 0.f; }
; #pragma unroll
;     for (int ks = 0; ks < KS; ++ks) {
;       const int kk = mp * 2 + ks;
;       const int key0 = r, key1 = 32 + r;
;       const int o0 = key0 * 128 + (((2 * kk + h2) ^ ((key0 >> 1) & 7)) << 4), o1 = key1 * 128 + (((2 * kk + h2) ^ ((key1 >> 1) & 7)) << 4);
;       SA0 = MFMA32(*(const bf16x8*)(sK + o0), qf[ks], SA0);
;       SA1 = MFMA32(*(const bf16x8*)(sK + o1), qf[ks], SA1);
;       SB0 = MFMA32(*(const bf16x8*)(sK + 16896 + o0), qf[ks], SB0);
;       SB1 = MFMA32(*(const bf16x8*)(sK + 16896 + o1), qf[ks], SB1);
;     }
; #pragma unroll
;     for (int hf = 0; hf < 2; ++hf) {
;     const unsigned char* sVc = sV + hf * 16896;
;     const int tbcur = tile_base(j + hf);
;     f32x16 S[2];
;     S[0] = hf == 0 ? SA0 : SB0;
;     S[1] = hf == 0 ? SA1 : SB1;
;     if (MODE == 1 && j + hf >= 4) {
;       const int iq = tq - NCTX;
;       const int jb = tbcur - NCTX;
; #pragma unroll
;       for (int mt = 0; mt < 2; ++mt)
; #pragma unroll
;         for (int i = 0; i < 16; ++i) {
;           const int dd = iq - (jb + mt * 32 + crow(i, h2));
;           if (dd > 128 || dd < -128) S[mt][i] = -1e30f;
;         }
;     }
;     float mx = -1e30f;
; #pragma unroll
;     for (int mt = 0; mt < 2; ++mt)
; #pragma unroll
;       for (int i = 0; i < 16; ++i) mx = fmaxf(mx, S[mt][i]);
;     mx = fmaxf(mx, __shfl_xor(mx, 32));
;     const float zmx = mx * cexp;
;     if (__any(zmx > mrun + 8.f)) {
;       const float mnew = fmaxf(mrun, zmx);
;       const float alpha = __builtin_amdgcn_exp2f(mrun - mnew);
;       mrun = mnew;
;       lsum *= alpha;
;       const f32x2 al2 = {alpha, alpha};
; #pragma unroll
;       for (int vt = 0; vt < 2; ++vt)
; #pragma unroll
;         for (int i = 0; i < 8; ++i) {
;           f32x2 o = {O[vt][2 * i], O[vt][2 * i + 1]};
.LBB0_580:
	v_add_u32_e32 v32, 0x2000, v144
	s_add_i32 s2, s2, 2
	s_waitcnt lgkmcnt(0)
	s_barrier
	s_waitcnt vmcnt(0)
	ds_write_b128 v141, v[104:107]
	ds_write_b128 v141, v[108:111] offset:4096
	ds_write2_b64 v32, v[120:121], v[122:123] offset1:1
	v_add_u32_e32 v32, 0x3100, v144
	s_cmp_ge_u32 s2, s4
	ds_write2_b64 v32, v[128:129], v[130:131] offset1:1
	ds_write_b128 v141, v[112:115] offset:16896
	ds_write_b128 v141, v[116:119] offset:20992
	v_add_u32_e32 v32, 0x6200, v144
	s_cselect_b64 s[0:1], -1, 0
	ds_write2_b64 v32, v[124:125], v[126:127] offset1:1
	v_add_u32_e32 v32, 0x7300, v144
	s_and_b64 vcc, exec, s[0:1]
	ds_write2_b64 v32, v[132:133], v[134:135] offset1:1
	s_waitcnt lgkmcnt(0)
	s_barrier
	ds_read_b128 v[204:207], v142
	ds_read_b128 v[208:211], v143
	ds_read_b128 v[212:215], v142 offset:4096
	ds_read_b128 v[216:219], v143 offset:4096
	ds_read_b128 v[220:223], v142 offset:16896
	ds_read_b128 v[224:227], v143 offset:16896
	ds_read_b128 v[228:231], v142 offset:20992
	ds_read_b128 v[232:235], v143 offset:20992
	s_cbranch_vccnz .LBB0_582
	v_lshl_add_u64 v[32:33], v[138:139], 0, v[160:161]
	v_add_co_u32_e32 v34, vcc, 0x42d7000, v32
	s_nop 1
	v_addc_co_u32_e32 v35, vcc, 0, v33, vcc
	v_add_co_u32_e32 v36, vcc, 0x431b000, v32
	s_nop 1
	v_addc_co_u32_e32 v37, vcc, 0, v33, vcc
	global_load_dwordx4 v[104:107], v[34:35], off offset:512
	global_load_dwordx4 v[108:111], v[36:37], off offset:1536
	v_lshl_add_u64 v[34:35], v[136:137], 0, v[160:161]
	v_add_co_u32_e32 v36, vcc, 0xef06000, v34
	s_nop 1
	v_addc_co_u32_e32 v37, vcc, 0, v35, vcc
	v_add_co_u32_e32 v34, vcc, 0xef2a000, v34
	s_nop 1
	v_addc_co_u32_e32 v35, vcc, 0, v35, vcc
	v_add_co_u32_e32 v38, vcc, 0x435f000, v32
	s_nop 1
	v_addc_co_u32_e32 v39, vcc, 0, v33, vcc
	v_add_co_u32_e32 v32, vcc, 0x43a3000, v32
	s_nop 1
	v_addc_co_u32_e32 v33, vcc, 0, v33, vcc
	global_load_dwordx4 v[112:115], v[38:39], off offset:2560
	global_load_dwordx4 v[116:119], v[32:33], off offset:3584
	global_load_dwordx4 v[120:123], v[36:37], off offset:256
	global_load_dwordx4 v[124:127], v[36:37], off offset:384
	global_load_dwordx4 v[128:131], v[34:35], off offset:256
	global_load_dwordx4 v[132:135], v[34:35], off offset:384
.LBB0_582:
	s_mov_b32 s5, 0xf149f2ca
	s_waitcnt lgkmcnt(6)
	v_mfma_f32_32x32x16_bf16 v[80:95], v[204:207], v[96:99], 0
	v_mfma_f32_32x32x16_bf16 v[80:95], v[208:211], v[100:103], v[80:95]
	s_waitcnt lgkmcnt(4)
	v_mfma_f32_32x32x16_bf16 v[64:79], v[212:215], v[96:99], 0
	v_mfma_f32_32x32x16_bf16 v[64:79], v[216:219], v[100:103], v[64:79]
	s_waitcnt lgkmcnt(2)
	v_mfma_f32_32x32x16_bf16 v[48:63], v[220:223], v[96:99], 0
	v_mfma_f32_32x32x16_bf16 v[48:63], v[224:227], v[100:103], v[48:63]
	s_waitcnt lgkmcnt(0)
	v_mfma_f32_32x32x16_bf16 v[32:47], v[228:231], v[96:99], 0
	v_mfma_f32_32x32x16_bf16 v[32:47], v[232:235], v[100:103], v[32:47]
	s_nop 2
	v_max3_f32 v146, v80, s5, v81
	v_max3_f32 v146, v146, v82, v83
	v_max3_f32 v146, v146, v84, v85
	v_max3_f32 v146, v146, v86, v87
	v_max3_f32 v146, v146, v88, v89
	v_max3_f32 v146, v146, v90, v91
	v_max3_f32 v146, v146, v92, v93
	v_max3_f32 v146, v146, v94, v95
	v_max3_f32 v146, v146, v64, v65
	v_max3_f32 v146, v146, v66, v67
	v_max3_f32 v146, v146, v68, v69
	v_max3_f32 v146, v146, v70, v71
	v_max3_f32 v146, v146, v72, v73
	v_max3_f32 v146, v146, v74, v75
	v_max3_f32 v146, v146, v76, v77
	v_max3_f32 v146, v146, v78, v79
	ds_bpermute_b32 v147, v170, v146
	s_waitcnt lgkmcnt(0)
	v_max_f32_e32 v147, v147, v147
	v_max_f32_e32 v146, v146, v147
	v_mul_f32_e32 v147, 0x3e8293ee, v146
	v_add_f32_e32 v146, 0x41000000, v140
	v_cmp_gt_f32_e32 vcc, v147, v146
	s_cbranch_vccz .LBB0_584
	v_max_f32_e32 v146, v147, v147
	v_max_f32_e32 v147, v140, v140
	v_max_f32_e32 v147, v147, v146
	v_sub_f32_e32 v140, v140, v147
	v_exp_f32_e32 v140, v140
	v_add_f32_e32 v146, 0x41000000, v147
	v_pk_mul_f32 v[18:19], v[18:19], v[140:141] op_sel_hi:[1,0]
	v_pk_mul_f32 v[20:21], v[20:21], v[140:141] op_sel_hi:[1,0]
	v_pk_mul_f32 v[22:23], v[22:23], v[140:141] op_sel_hi:[1,0]
	v_pk_mul_f32 v[24:25], v[24:25], v[140:141] op_sel_hi:[1,0]
	v_pk_mul_f32 v[26:27], v[26:27], v[140:141] op_sel_hi:[1,0]
	v_pk_mul_f32 v[28:29], v[28:29], v[140:141] op_sel_hi:[1,0]
	v_pk_mul_f32 v[16:17], v[16:17], v[140:141] op_sel_hi:[1,0]
	v_pk_mul_f32 v[30:31], v[30:31], v[140:141] op_sel_hi:[1,0]
	v_pk_mul_f32 v[0:1], v[0:1], v[140:141] op_sel_hi:[1,0]
	v_pk_mul_f32 v[2:3], v[2:3], v[140:141] op_sel_hi:[1,0]
	v_pk_mul_f32 v[4:5], v[4:5], v[140:141] op_sel_hi:[1,0]
	v_pk_mul_f32 v[6:7], v[6:7], v[140:141] op_sel_hi:[1,0]
	v_pk_mul_f32 v[8:9], v[8:9], v[140:141] op_sel_hi:[1,0]
	v_pk_mul_f32 v[10:11], v[10:11], v[140:141] op_sel_hi:[1,0]
	v_pk_mul_f32 v[12:13], v[12:13], v[140:141] op_sel_hi:[1,0]
	v_pk_mul_f32 v[14:15], v[14:15], v[140:141] op_sel_hi:[1,0]
	v_mul_f32_e32 v200, v200, v140
	v_mov_b32_e32 v140, v147
; DI unsigned pk2(float a, float b) { hwf32x2 f = {a, b}; hwbf16x2 r = __builtin_convertvector(f, hwbf16x2); return __builtin_bit_cast(unsigned, r); }
; #define MFMA32(a, b, c) __builtin_amdgcn_mfma_f32_32x32x16_bf16((a), (b), (c), 0, 0, 0)
; template <int MODE>
; DI void attn_mfma(const Params& p, int l, int b, int hd, int qb, unsigned char* smem) {
;     ...
;     float mx = -1e30f;
; #pragma unroll
;     for (int mt = 0; mt < 2; ++mt)
; #pragma unroll
;       for (int i = 0; i < 16; ++i) mx = fmaxf(mx, S[mt][i]);
;     mx = fmaxf(mx, __shfl_xor(mx, 32));
;     const float zmx = mx * cexp;
;     if (__any(zmx > mrun + 8.f)) {
;       const float mnew = fmaxf(mrun, zmx);
;       const float alpha = __builtin_amdgcn_exp2f(mrun - mnew);
;       mrun = mnew;
;       lsum *= alpha;
;       const f32x2 al2 = {alpha, alpha};
; #pragma unroll
;       for (int vt = 0; vt < 2; ++vt)
; #pragma unroll
;         for (int i = 0; i < 8; ++i) {
;           f32x2 o = {O[vt][2 * i], O[vt][2 * i + 1]};
;           o = o * al2;
;           O[vt][2 * i] = o.x; O[vt][2 * i + 1] = o.y;
;         }
;     }
;     const f32x2 c2 = {cexp, cexp}, m2 = {mrun, mrun};
;     f32x2 ps2 = {0.f, 0.f};
;     unsigned pk[2][8];
; #pragma unroll
;     for (int mt = 0; mt < 2; ++mt)
; #pragma unroll
;       for (int i = 0; i < 8; ++i) {
;         f32x2 z = {S[mt][2 * i], S[mt][2 * i + 1]};
;         z = z * c2 - m2;
;         f32x2 pv = {__builtin_amdgcn_exp2f(z.x), __builtin_amdgcn_exp2f(z.y)};
;         ps2 = ps2 + pv;
;         pk[mt][i] = pk2(pv.x, pv.y);
;       }
;     lsum += ps2.x + ps2.y;
; #pragma unroll
;     for (int mt = 0; mt < 2; ++mt)
; #pragma unroll
;       for (int s = 0; s < 2; ++s) {
;         const uint4 pu = make_uint4(pk[mt][4 * s], pk[mt][4 * s + 1], pk[mt][4 * s + 2], pk[mt][4 * s + 3]);
;         const bf16x8 pf = __builtin_bit_cast(bf16x8, pu);
; #pragma unroll
;         for (int vt = 0; vt < 2; ++vt) {
;           const unsigned char* bp = sVc + (vt * 32 + r) * 136 + (mt * 32 + 16 * s + 4 * h2) * 2;
;           const uint2 lo = *(const uint2*)(bp);
;           const uint2 hi = *(const uint2*)(bp + 16);
;           const uint4 u = make_uint4(lo.x, lo.y, hi.x, hi.y);
;           O[vt] = MFMA32(__builtin_bit_cast(bf16x8, u), pf, O[vt]);
;         }
;       }
.LBB0_584:
	ds_read2_b64 v[204:207], v236 offset1:2
	ds_read2_b64 v[208:211], v237 offset0:32 offset1:34
	ds_read2_b64 v[212:215], v236 offset0:4 offset1:6
	ds_read2_b64 v[216:219], v237 offset0:36 offset1:38
	ds_read2_b64 v[220:223], v236 offset0:8 offset1:10
	ds_read2_b64 v[224:227], v237 offset0:40 offset1:42
	ds_read2_b64 v[228:231], v236 offset0:12 offset1:14
	ds_read2_b64 v[232:235], v237 offset0:44 offset1:46
	s_mov_b32 s8, 0x3e8293ee
	v_fma_f32 v80, v80, s8, -v140
	v_fma_f32 v81, v81, s8, -v140
	v_fma_f32 v82, v82, s8, -v140
	v_fma_f32 v83, v83, s8, -v140
	v_exp_f32_e32 v80, v80
	v_exp_f32_e32 v81, v81
	v_exp_f32_e32 v82, v82
	v_exp_f32_e32 v83, v83
	v_fma_f32 v86, v86, s8, -v140
	v_fma_f32 v87, v87, s8, -v140
	v_add_f32_e64 v148, v80, 0
	v_add_f32_e64 v149, v81, 0
	v_cvt_pk_bf16_f32 v80, v80, v81
	v_add_f32_e64 v148, v82, v148
	v_add_f32_e64 v149, v83, v149
	v_cvt_pk_bf16_f32 v81, v82, v83
	v_fma_f32 v82, v84, s8, -v140
	v_fma_f32 v83, v85, s8, -v140
	v_exp_f32_e32 v86, v86
	v_exp_f32_e32 v82, v82
	v_exp_f32_e32 v83, v83
	v_exp_f32_e32 v87, v87
	v_fma_f32 v64, v64, s8, -v140
	v_fma_f32 v65, v65, s8, -v140
	v_add_f32_e64 v84, v82, v148
	v_add_f32_e64 v85, v83, v149
	v_cvt_pk_bf16_f32 v82, v82, v83
	v_add_f32_e64 v84, v86, v84
	v_add_f32_e64 v85, v87, v85
	v_cvt_pk_bf16_f32 v83, v86, v87
	v_fma_f32 v86, v88, s8, -v140
	v_fma_f32 v87, v89, s8, -v140
	v_exp_f32_e32 v64, v64
	v_exp_f32_e32 v86, v86
	v_exp_f32_e32 v87, v87
	v_exp_f32_e32 v65, v65
	v_add_f32_e64 v84, v86, v84
	v_add_f32_e64 v85, v87, v85
	v_cvt_pk_bf16_f32 v88, v86, v87
	v_fma_f32 v86, v90, s8, -v140
	v_fma_f32 v87, v91, s8, -v140
	s_nop 0
	v_exp_f32_e32 v86, v86
	v_exp_f32_e32 v87, v87
	s_nop 0
	v_add_f32_e64 v84, v86, v84
	v_add_f32_e64 v85, v87, v85
	v_cvt_pk_bf16_f32 v89, v86, v87
	v_fma_f32 v86, v92, s8, -v140
	v_fma_f32 v87, v93, s8, -v140
	s_nop 0
	v_exp_f32_e32 v86, v86
	v_exp_f32_e32 v87, v87
	s_nop 0
	v_add_f32_e64 v84, v86, v84
	v_add_f32_e64 v85, v87, v85
	v_cvt_pk_bf16_f32 v90, v86, v87
	v_fma_f32 v86, v94, s8, -v140
	v_fma_f32 v87, v95, s8, -v140
	s_nop 0
	v_exp_f32_e32 v86, v86
	v_exp_f32_e32 v87, v87
	s_nop 0
	v_add_f32_e64 v84, v86, v84
	v_add_f32_e64 v85, v87, v85
	v_cvt_pk_bf16_f32 v91, v86, v87
	v_add_f32_e64 v86, v64, v84
	v_add_f32_e64 v87, v65, v85
	v_cvt_pk_bf16_f32 v84, v64, v65
	v_fma_f32 v64, v66, s8, -v140
	v_fma_f32 v65, v67, s8, -v140
	s_nop 0
	v_exp_f32_e32 v64, v64
	v_exp_f32_e32 v65, v65
	s_nop 0
	v_add_f32_e64 v66, v64, v86
	v_add_f32_e64 v67, v65, v87
	v_cvt_pk_bf16_f32 v85, v64, v65
	v_fma_f32 v64, v68, s8, -v140
	v_fma_f32 v65, v69, s8, -v140
	v_fma_f32 v68, v74, s8, -v140
	v_fma_f32 v69, v75, s8, -v140
	v_exp_f32_e32 v64, v64
	v_exp_f32_e32 v65, v65
	v_exp_f32_e32 v68, v68
	v_exp_f32_e32 v69, v69
	v_add_f32_e64 v66, v64, v66
	v_add_f32_e64 v67, v65, v67
	v_cvt_pk_bf16_f32 v86, v64, v65
	v_fma_f32 v64, v70, s8, -v140
	v_fma_f32 v65, v71, s8, -v140
	s_nop 0
	v_exp_f32_e32 v64, v64
	v_exp_f32_e32 v65, v65
	s_nop 0
	v_add_f32_e64 v66, v64, v66
	v_add_f32_e64 v67, v65, v67
	v_cvt_pk_bf16_f32 v87, v64, v65
	v_fma_f32 v64, v72, s8, -v140
	v_fma_f32 v65, v73, s8, -v140
	s_nop 0
	v_exp_f32_e32 v64, v64
	v_exp_f32_e32 v65, v65
	s_nop 0
	v_add_f32_e64 v66, v64, v66
	v_add_f32_e64 v67, v65, v67
	v_cvt_pk_bf16_f32 v64, v64, v65
	v_add_f32_e64 v66, v68, v66
	v_add_f32_e64 v67, v69, v67
	v_cvt_pk_bf16_f32 v65, v68, v69
	v_fma_f32 v68, v76, s8, -v140
	v_fma_f32 v69, v77, s8, -v140
	s_nop 0
	v_exp_f32_e32 v68, v68
	v_exp_f32_e32 v69, v69
	s_nop 0
	v_add_f32_e64 v70, v68, v66
	v_add_f32_e64 v71, v69, v67
	v_cvt_pk_bf16_f32 v66, v68, v69
	v_fma_f32 v68, v78, s8, -v140
	v_fma_f32 v69, v79, s8, -v140
	s_nop 0
	v_exp_f32_e32 v72, v68
	v_exp_f32_e32 v73, v69
	s_nop 0
	v_add_f32_e64 v68, v72, v70
	v_add_f32_e64 v69, v73, v71
	v_cvt_pk_bf16_f32 v67, v72, v73
	s_waitcnt lgkmcnt(0)
	v_mfma_f32_32x32x16_bf16 v[16:31], v[204:207], v[80:83], v[16:31]
	v_mfma_f32_32x32x16_bf16 v[0:15], v[208:211], v[80:83], v[0:15]
	v_mfma_f32_32x32x16_bf16 v[16:31], v[212:215], v[88:91], v[16:31]
	v_mfma_f32_32x32x16_bf16 v[0:15], v[216:219], v[88:91], v[0:15]
	v_mfma_f32_32x32x16_bf16 v[16:31], v[220:223], v[84:87], v[16:31]
	v_mfma_f32_32x32x16_bf16 v[0:15], v[224:227], v[84:87], v[0:15]
	v_mfma_f32_32x32x16_bf16 v[16:31], v[228:231], v[64:67], v[16:31]
	v_mfma_f32_32x32x16_bf16 v[0:15], v[232:235], v[64:67], v[0:15]
	v_add_f32_e32 v64, v68, v69
	v_add_f32_e32 v66, v200, v64
	v_max3_f32 v64, v48, s5, v49
	v_max3_f32 v64, v64, v50, v51
	v_max3_f32 v64, v64, v52, v53
	v_max3_f32 v64, v64, v54, v55
	v_max3_f32 v64, v64, v56, v57
	v_max3_f32 v64, v64, v58, v59
	v_max3_f32 v64, v64, v60, v61
	v_max3_f32 v64, v64, v62, v63
	v_max3_f32 v64, v64, v32, v33
	v_max3_f32 v64, v64, v34, v35
	v_max3_f32 v64, v64, v36, v37
	v_max3_f32 v64, v64, v38, v39
	v_max3_f32 v64, v64, v40, v41
	v_max3_f32 v64, v64, v42, v43
	v_max3_f32 v64, v64, v44, v45
	v_max3_f32 v64, v64, v46, v47
	ds_bpermute_b32 v65, v170, v64
	s_waitcnt lgkmcnt(0)
	v_max_f32_e32 v65, v65, v65
	v_max_f32_e32 v64, v64, v65
	v_mul_f32_e32 v64, 0x3e8293ee, v64
	v_cmp_gt_f32_e32 vcc, v64, v146
	s_cbranch_vccnz .LBB0_578
	v_mov_b64_e32 v[64:65], v[140:141]
	s_branch .LBB0_579
